# split P1->P2 island barrier: per-wave arrive after the norm pass (inside the CV block), poll after CV
# speedup vs baseline: 1.0129x; 1.0071x over previous
.LBB0_443:
	v_readlane_b32 s0, v254, 8
	v_readlane_b32 s1, v254, 9
	v_readlane_b32 s2, v254, 20
	v_mbcnt_lo_u32_b32 v0, -1, 0
	v_mbcnt_hi_u32_b32 v0, -1, v0
	s_and_b32 s3, s2, 7
	s_lshr_b32 s4, s2, 3
	s_lshl_b32 s5, s4, 3
	s_add_i32 s5, s5, s69
	v_lshlrev_b32_e32 v1, 5, v0
	v_lshlrev_b32_e32 v4, 6, v0
	v_and_b32_e32 v9, 1, v0
	v_lshrrev_b32_e32 v10, 1, v0
	v_mul_u32_u24_e32 v13, 0x900, v9
	v_mul_u32_u24_e32 v14, 0x1600, v9
	v_lshl_add_u32 v13, v10, 8, v13
	v_lshl_add_u32 v14, v10, 8, v14
	s_mul_i32 s8, s3, 0x12000
	s_add_u32 s10, s0, s8
	s_addc_u32 s11, s1, 0
	s_add_u32 s10, s10, 0x100000
	s_addc_u32 s11, s11, 0
	s_add_u32 s22, s10, 12288
	s_addc_u32 s23, s11, 0
	global_load_dwordx4 v[100:103], v4, s[22:23]
	global_load_dwordx4 v[104:107], v4, s[22:23] offset:16
	global_load_dwordx4 v[108:111], v4, s[22:23] offset:32
	global_load_dwordx4 v[112:115], v4, s[22:23] offset:48
	s_add_u32 s22, s22, 0x9000
	s_addc_u32 s23, s23, 0
	global_load_dwordx4 v[116:119], v4, s[22:23]
	global_load_dwordx4 v[120:123], v4, s[22:23] offset:16
	global_load_dwordx4 v[124:127], v4, s[22:23] offset:32
	global_load_dwordx4 v[128:131], v4, s[22:23] offset:48
	s_add_u32 s22, s10, 24576
	s_addc_u32 s23, s11, 0
	global_load_dwordx4 v[16:19], v4, s[22:23]
	global_load_dwordx4 v[20:23], v4, s[22:23] offset:16
	global_load_dwordx4 v[24:27], v4, s[22:23] offset:32
	global_load_dwordx4 v[28:31], v4, s[22:23] offset:48
	s_add_u32 s22, s22, 0x9000
	s_addc_u32 s23, s23, 0
	global_load_dwordx4 v[32:35], v4, s[22:23]
	global_load_dwordx4 v[36:39], v4, s[22:23] offset:16
	global_load_dwordx4 v[40:43], v4, s[22:23] offset:32
	global_load_dwordx4 v[44:47], v4, s[22:23] offset:48
	s_lshl_b32 s8, s5, 11
	s_add_u32 s28, s0, s8
	s_addc_u32 s29, s1, 0
	s_add_u32 s28, s28, 0x3200000
	s_addc_u32 s29, s29, 0
	global_load_dwordx4 v[132:135], v1, s[28:29]
	global_load_dwordx4 v[136:139], v1, s[28:29] offset:16
	s_add_u32 s28, s28, 0x80000
	s_addc_u32 s29, s29, 0
	global_load_dwordx4 v[140:143], v1, s[28:29]
	global_load_dwordx4 v[144:147], v1, s[28:29] offset:16
	s_add_u32 s28, s28, 0x80000
	s_addc_u32 s29, s29, 0
	global_load_dwordx4 v[148:151], v1, s[28:29]
	global_load_dwordx4 v[152:155], v1, s[28:29] offset:16
	s_add_u32 s28, s28, 0x80000
	s_addc_u32 s29, s29, 0
	global_load_dwordx4 v[156:159], v1, s[28:29]
	global_load_dwordx4 v[160:163], v1, s[28:29] offset:16
	s_add_u32 s28, s28, 0x80000
	s_addc_u32 s29, s29, 0
	global_load_dwordx4 v[164:167], v1, s[28:29]
	global_load_dwordx4 v[168:171], v1, s[28:29] offset:16
	s_add_u32 s28, s28, 0x80000
	s_addc_u32 s29, s29, 0
	global_load_dwordx4 v[172:175], v1, s[28:29]
	global_load_dwordx4 v[176:179], v1, s[28:29] offset:16
	s_add_u32 s28, s28, 0x80000
	s_addc_u32 s29, s29, 0
	global_load_dwordx4 v[180:183], v1, s[28:29]
	global_load_dwordx4 v[184:187], v1, s[28:29] offset:16
	s_add_u32 s28, s28, 0x80000
	s_addc_u32 s29, s29, 0
	global_load_dwordx4 v[188:191], v1, s[28:29]
	global_load_dwordx4 v[192:195], v1, s[28:29] offset:16
	s_add_u32 s28, s28, 0x80000
	s_addc_u32 s29, s29, 0
	global_load_dwordx4 v[196:199], v1, s[28:29]
	global_load_dwordx4 v[200:203], v1, s[28:29] offset:16
	s_add_u32 s28, s28, 0x80000
	s_addc_u32 s29, s29, 0
	s_waitcnt vmcnt(0)
	s_lshl_b32 s8, s3, 8
	s_add_u32 s8, s0, s8
	s_addc_u32 s9, s1, 0
	v_mov_b32_e32 v15, 0
	v_mov_b32_e32 v11, 1
	s_mov_b64 exec, 1
	global_atomic_add v15, v11, s[8:9] offset:2112
	s_mov_b64 exec, -1
	v_lshlrev_b32_e32 v5, 16, v132
	v_and_b32_e32 v6, 0xffff0000, v132
	v_mul_f32_e32 v212, v100, v5
	v_mul_f32_e32 v213, v116, v5
	v_fmac_f32_e32 v212, v101, v6
	v_fmac_f32_e32 v213, v117, v6
	v_lshlrev_b32_e32 v7, 16, v140
	v_and_b32_e32 v8, 0xffff0000, v140
	v_mul_f32_e32 v214, v100, v7
	v_mul_f32_e32 v215, v116, v7
	v_fmac_f32_e32 v214, v101, v8
	v_fmac_f32_e32 v215, v117, v8
	v_lshlrev_b32_e32 v5, 16, v148
	v_and_b32_e32 v6, 0xffff0000, v148
	v_mul_f32_e32 v216, v100, v5
	v_mul_f32_e32 v217, v116, v5
	v_fmac_f32_e32 v216, v101, v6
	v_fmac_f32_e32 v217, v117, v6
	v_lshlrev_b32_e32 v7, 16, v156
	v_and_b32_e32 v8, 0xffff0000, v156
	v_mul_f32_e32 v218, v100, v7
	v_mul_f32_e32 v219, v116, v7
	v_fmac_f32_e32 v218, v101, v8
	v_fmac_f32_e32 v219, v117, v8
	v_lshlrev_b32_e32 v5, 16, v164
	v_and_b32_e32 v6, 0xffff0000, v164
	v_mul_f32_e32 v220, v100, v5
	v_mul_f32_e32 v221, v116, v5
	v_fmac_f32_e32 v220, v101, v6
	v_fmac_f32_e32 v221, v117, v6
	v_lshlrev_b32_e32 v7, 16, v172
	v_and_b32_e32 v8, 0xffff0000, v172
	v_mul_f32_e32 v222, v100, v7
	v_mul_f32_e32 v223, v116, v7
	v_fmac_f32_e32 v222, v101, v8
	v_fmac_f32_e32 v223, v117, v8
	v_lshlrev_b32_e32 v5, 16, v180
	v_and_b32_e32 v6, 0xffff0000, v180
	v_mul_f32_e32 v224, v100, v5
	v_mul_f32_e32 v225, v116, v5
	v_fmac_f32_e32 v224, v101, v6
	v_fmac_f32_e32 v225, v117, v6
	v_lshlrev_b32_e32 v7, 16, v188
	v_and_b32_e32 v8, 0xffff0000, v188
	v_mul_f32_e32 v226, v100, v7
	v_mul_f32_e32 v227, v116, v7
	v_fmac_f32_e32 v226, v101, v8
	v_fmac_f32_e32 v227, v117, v8
	v_lshlrev_b32_e32 v5, 16, v196
	v_and_b32_e32 v6, 0xffff0000, v196
	v_mul_f32_e32 v228, v100, v5
	v_mul_f32_e32 v229, v116, v5
	v_fmac_f32_e32 v228, v101, v6
	v_fmac_f32_e32 v229, v117, v6
	v_lshlrev_b32_e32 v5, 16, v133
	v_and_b32_e32 v6, 0xffff0000, v133
	v_fmac_f32_e32 v212, v102, v5
	v_fmac_f32_e32 v213, v118, v5
	v_fmac_f32_e32 v212, v103, v6
	v_fmac_f32_e32 v213, v119, v6
	v_lshlrev_b32_e32 v7, 16, v141
	v_and_b32_e32 v8, 0xffff0000, v141
	v_fmac_f32_e32 v214, v102, v7
	v_fmac_f32_e32 v215, v118, v7
	v_fmac_f32_e32 v214, v103, v8
	v_fmac_f32_e32 v215, v119, v8
	v_lshlrev_b32_e32 v5, 16, v149
	v_and_b32_e32 v6, 0xffff0000, v149
	v_fmac_f32_e32 v216, v102, v5
	v_fmac_f32_e32 v217, v118, v5
	v_fmac_f32_e32 v216, v103, v6
	v_fmac_f32_e32 v217, v119, v6
	v_lshlrev_b32_e32 v7, 16, v157
	v_and_b32_e32 v8, 0xffff0000, v157
	v_fmac_f32_e32 v218, v102, v7
	v_fmac_f32_e32 v219, v118, v7
	v_fmac_f32_e32 v218, v103, v8
	v_fmac_f32_e32 v219, v119, v8
	v_lshlrev_b32_e32 v5, 16, v165
	v_and_b32_e32 v6, 0xffff0000, v165
	v_fmac_f32_e32 v220, v102, v5
	v_fmac_f32_e32 v221, v118, v5
	v_fmac_f32_e32 v220, v103, v6
	v_fmac_f32_e32 v221, v119, v6
	v_lshlrev_b32_e32 v7, 16, v173
	v_and_b32_e32 v8, 0xffff0000, v173
	v_fmac_f32_e32 v222, v102, v7
	v_fmac_f32_e32 v223, v118, v7
	v_fmac_f32_e32 v222, v103, v8
	v_fmac_f32_e32 v223, v119, v8
	v_lshlrev_b32_e32 v5, 16, v181
	v_and_b32_e32 v6, 0xffff0000, v181
	v_fmac_f32_e32 v224, v102, v5
	v_fmac_f32_e32 v225, v118, v5
	v_fmac_f32_e32 v224, v103, v6
	v_fmac_f32_e32 v225, v119, v6
	v_lshlrev_b32_e32 v7, 16, v189
	v_and_b32_e32 v8, 0xffff0000, v189
	v_fmac_f32_e32 v226, v102, v7
	v_fmac_f32_e32 v227, v118, v7
	v_fmac_f32_e32 v226, v103, v8
	v_fmac_f32_e32 v227, v119, v8
	v_lshlrev_b32_e32 v5, 16, v197
	v_and_b32_e32 v6, 0xffff0000, v197
	v_fmac_f32_e32 v228, v102, v5
	v_fmac_f32_e32 v229, v118, v5
	v_fmac_f32_e32 v228, v103, v6
	v_fmac_f32_e32 v229, v119, v6
	v_lshlrev_b32_e32 v5, 16, v134
	v_and_b32_e32 v6, 0xffff0000, v134
	v_fmac_f32_e32 v212, v104, v5
	v_fmac_f32_e32 v213, v120, v5
	v_fmac_f32_e32 v212, v105, v6
	v_fmac_f32_e32 v213, v121, v6
	v_lshlrev_b32_e32 v7, 16, v142
	v_and_b32_e32 v8, 0xffff0000, v142
	v_fmac_f32_e32 v214, v104, v7
	v_fmac_f32_e32 v215, v120, v7
	v_fmac_f32_e32 v214, v105, v8
	v_fmac_f32_e32 v215, v121, v8
	v_lshlrev_b32_e32 v5, 16, v150
	v_and_b32_e32 v6, 0xffff0000, v150
	v_fmac_f32_e32 v216, v104, v5
	v_fmac_f32_e32 v217, v120, v5
	v_fmac_f32_e32 v216, v105, v6
	v_fmac_f32_e32 v217, v121, v6
	v_lshlrev_b32_e32 v7, 16, v158
	v_and_b32_e32 v8, 0xffff0000, v158
	v_fmac_f32_e32 v218, v104, v7
	v_fmac_f32_e32 v219, v120, v7
	v_fmac_f32_e32 v218, v105, v8
	v_fmac_f32_e32 v219, v121, v8
	v_lshlrev_b32_e32 v5, 16, v166
	v_and_b32_e32 v6, 0xffff0000, v166
	v_fmac_f32_e32 v220, v104, v5
	v_fmac_f32_e32 v221, v120, v5
	v_fmac_f32_e32 v220, v105, v6
	v_fmac_f32_e32 v221, v121, v6
	v_lshlrev_b32_e32 v7, 16, v174
	v_and_b32_e32 v8, 0xffff0000, v174
	v_fmac_f32_e32 v222, v104, v7
	v_fmac_f32_e32 v223, v120, v7
	v_fmac_f32_e32 v222, v105, v8
	v_fmac_f32_e32 v223, v121, v8
	v_lshlrev_b32_e32 v5, 16, v182
	v_and_b32_e32 v6, 0xffff0000, v182
	v_fmac_f32_e32 v224, v104, v5
	v_fmac_f32_e32 v225, v120, v5
	v_fmac_f32_e32 v224, v105, v6
	v_fmac_f32_e32 v225, v121, v6
	v_lshlrev_b32_e32 v7, 16, v190
	v_and_b32_e32 v8, 0xffff0000, v190
	v_fmac_f32_e32 v226, v104, v7
	v_fmac_f32_e32 v227, v120, v7
	v_fmac_f32_e32 v226, v105, v8
	v_fmac_f32_e32 v227, v121, v8
	v_lshlrev_b32_e32 v5, 16, v198
	v_and_b32_e32 v6, 0xffff0000, v198
	v_fmac_f32_e32 v228, v104, v5
	v_fmac_f32_e32 v229, v120, v5
	v_fmac_f32_e32 v228, v105, v6
	v_fmac_f32_e32 v229, v121, v6
	v_lshlrev_b32_e32 v5, 16, v135
	v_and_b32_e32 v6, 0xffff0000, v135
	v_fmac_f32_e32 v212, v106, v5
	v_fmac_f32_e32 v213, v122, v5
	v_fmac_f32_e32 v212, v107, v6
	v_fmac_f32_e32 v213, v123, v6
	v_lshlrev_b32_e32 v7, 16, v143
	v_and_b32_e32 v8, 0xffff0000, v143
	v_fmac_f32_e32 v214, v106, v7
	v_fmac_f32_e32 v215, v122, v7
	v_fmac_f32_e32 v214, v107, v8
	v_fmac_f32_e32 v215, v123, v8
	v_lshlrev_b32_e32 v5, 16, v151
	v_and_b32_e32 v6, 0xffff0000, v151
	v_fmac_f32_e32 v216, v106, v5
	v_fmac_f32_e32 v217, v122, v5
	v_fmac_f32_e32 v216, v107, v6
	v_fmac_f32_e32 v217, v123, v6
	v_lshlrev_b32_e32 v7, 16, v159
	v_and_b32_e32 v8, 0xffff0000, v159
	v_fmac_f32_e32 v218, v106, v7
	v_fmac_f32_e32 v219, v122, v7
	v_fmac_f32_e32 v218, v107, v8
	v_fmac_f32_e32 v219, v123, v8
	v_lshlrev_b32_e32 v5, 16, v167
	v_and_b32_e32 v6, 0xffff0000, v167
	v_fmac_f32_e32 v220, v106, v5
	v_fmac_f32_e32 v221, v122, v5
	v_fmac_f32_e32 v220, v107, v6
	v_fmac_f32_e32 v221, v123, v6
	v_lshlrev_b32_e32 v7, 16, v175
	v_and_b32_e32 v8, 0xffff0000, v175
	v_fmac_f32_e32 v222, v106, v7
	v_fmac_f32_e32 v223, v122, v7
	v_fmac_f32_e32 v222, v107, v8
	v_fmac_f32_e32 v223, v123, v8
	v_lshlrev_b32_e32 v5, 16, v183
	v_and_b32_e32 v6, 0xffff0000, v183
	v_fmac_f32_e32 v224, v106, v5
	v_fmac_f32_e32 v225, v122, v5
	v_fmac_f32_e32 v224, v107, v6
	v_fmac_f32_e32 v225, v123, v6
	v_lshlrev_b32_e32 v7, 16, v191
	v_and_b32_e32 v8, 0xffff0000, v191
	v_fmac_f32_e32 v226, v106, v7
	v_fmac_f32_e32 v227, v122, v7
	v_fmac_f32_e32 v226, v107, v8
	v_fmac_f32_e32 v227, v123, v8
	v_lshlrev_b32_e32 v5, 16, v199
	v_and_b32_e32 v6, 0xffff0000, v199
	v_fmac_f32_e32 v228, v106, v5
	v_fmac_f32_e32 v229, v122, v5
	v_fmac_f32_e32 v228, v107, v6
	v_fmac_f32_e32 v229, v123, v6
	v_lshlrev_b32_e32 v5, 16, v136
	v_and_b32_e32 v6, 0xffff0000, v136
	v_fmac_f32_e32 v212, v108, v5
	v_fmac_f32_e32 v213, v124, v5
	v_fmac_f32_e32 v212, v109, v6
	v_fmac_f32_e32 v213, v125, v6
	v_lshlrev_b32_e32 v7, 16, v144
	v_and_b32_e32 v8, 0xffff0000, v144
	v_fmac_f32_e32 v214, v108, v7
	v_fmac_f32_e32 v215, v124, v7
	v_fmac_f32_e32 v214, v109, v8
	v_fmac_f32_e32 v215, v125, v8
	v_lshlrev_b32_e32 v5, 16, v152
	v_and_b32_e32 v6, 0xffff0000, v152
	v_fmac_f32_e32 v216, v108, v5
	v_fmac_f32_e32 v217, v124, v5
	v_fmac_f32_e32 v216, v109, v6
	v_fmac_f32_e32 v217, v125, v6
	v_lshlrev_b32_e32 v7, 16, v160
	v_and_b32_e32 v8, 0xffff0000, v160
	v_fmac_f32_e32 v218, v108, v7
	v_fmac_f32_e32 v219, v124, v7
	v_fmac_f32_e32 v218, v109, v8
	v_fmac_f32_e32 v219, v125, v8
	v_lshlrev_b32_e32 v5, 16, v168
	v_and_b32_e32 v6, 0xffff0000, v168
	v_fmac_f32_e32 v220, v108, v5
	v_fmac_f32_e32 v221, v124, v5
	v_fmac_f32_e32 v220, v109, v6
	v_fmac_f32_e32 v221, v125, v6
	v_lshlrev_b32_e32 v7, 16, v176
	v_and_b32_e32 v8, 0xffff0000, v176
	v_fmac_f32_e32 v222, v108, v7
	v_fmac_f32_e32 v223, v124, v7
	v_fmac_f32_e32 v222, v109, v8
	v_fmac_f32_e32 v223, v125, v8
	v_lshlrev_b32_e32 v5, 16, v184
	v_and_b32_e32 v6, 0xffff0000, v184
	v_fmac_f32_e32 v224, v108, v5
	v_fmac_f32_e32 v225, v124, v5
	v_fmac_f32_e32 v224, v109, v6
	v_fmac_f32_e32 v225, v125, v6
	v_lshlrev_b32_e32 v7, 16, v192
	v_and_b32_e32 v8, 0xffff0000, v192
	v_fmac_f32_e32 v226, v108, v7
	v_fmac_f32_e32 v227, v124, v7
	v_fmac_f32_e32 v226, v109, v8
	v_fmac_f32_e32 v227, v125, v8
	v_lshlrev_b32_e32 v5, 16, v200
	v_and_b32_e32 v6, 0xffff0000, v200
	v_fmac_f32_e32 v228, v108, v5
	v_fmac_f32_e32 v229, v124, v5
	v_fmac_f32_e32 v228, v109, v6
	v_fmac_f32_e32 v229, v125, v6
	v_lshlrev_b32_e32 v5, 16, v137
	v_and_b32_e32 v6, 0xffff0000, v137
	v_fmac_f32_e32 v212, v110, v5
	v_fmac_f32_e32 v213, v126, v5
	v_fmac_f32_e32 v212, v111, v6
	v_fmac_f32_e32 v213, v127, v6
	v_lshlrev_b32_e32 v7, 16, v145
	v_and_b32_e32 v8, 0xffff0000, v145
	v_fmac_f32_e32 v214, v110, v7
	v_fmac_f32_e32 v215, v126, v7
	v_fmac_f32_e32 v214, v111, v8
	v_fmac_f32_e32 v215, v127, v8
	v_lshlrev_b32_e32 v5, 16, v153
	v_and_b32_e32 v6, 0xffff0000, v153
	v_fmac_f32_e32 v216, v110, v5
	v_fmac_f32_e32 v217, v126, v5
	v_fmac_f32_e32 v216, v111, v6
	v_fmac_f32_e32 v217, v127, v6
	v_lshlrev_b32_e32 v7, 16, v161
	v_and_b32_e32 v8, 0xffff0000, v161
	v_fmac_f32_e32 v218, v110, v7
	v_fmac_f32_e32 v219, v126, v7
	v_fmac_f32_e32 v218, v111, v8
	v_fmac_f32_e32 v219, v127, v8
	v_lshlrev_b32_e32 v5, 16, v169
	v_and_b32_e32 v6, 0xffff0000, v169
	v_fmac_f32_e32 v220, v110, v5
	v_fmac_f32_e32 v221, v126, v5
	v_fmac_f32_e32 v220, v111, v6
	v_fmac_f32_e32 v221, v127, v6
	v_lshlrev_b32_e32 v7, 16, v177
	v_and_b32_e32 v8, 0xffff0000, v177
	v_fmac_f32_e32 v222, v110, v7
	v_fmac_f32_e32 v223, v126, v7
	v_fmac_f32_e32 v222, v111, v8
	v_fmac_f32_e32 v223, v127, v8
	v_lshlrev_b32_e32 v5, 16, v185
	v_and_b32_e32 v6, 0xffff0000, v185
	v_fmac_f32_e32 v224, v110, v5
	v_fmac_f32_e32 v225, v126, v5
	v_fmac_f32_e32 v224, v111, v6
	v_fmac_f32_e32 v225, v127, v6
	v_lshlrev_b32_e32 v7, 16, v193
	v_and_b32_e32 v8, 0xffff0000, v193
	v_fmac_f32_e32 v226, v110, v7
	v_fmac_f32_e32 v227, v126, v7
	v_fmac_f32_e32 v226, v111, v8
	v_fmac_f32_e32 v227, v127, v8
	v_lshlrev_b32_e32 v5, 16, v201
	v_and_b32_e32 v6, 0xffff0000, v201
	v_fmac_f32_e32 v228, v110, v5
	v_fmac_f32_e32 v229, v126, v5
	v_fmac_f32_e32 v228, v111, v6
	v_fmac_f32_e32 v229, v127, v6
	v_lshlrev_b32_e32 v5, 16, v138
	v_and_b32_e32 v6, 0xffff0000, v138
	v_fmac_f32_e32 v212, v112, v5
	v_fmac_f32_e32 v213, v128, v5
	v_fmac_f32_e32 v212, v113, v6
	v_fmac_f32_e32 v213, v129, v6
	v_lshlrev_b32_e32 v7, 16, v146
	v_and_b32_e32 v8, 0xffff0000, v146
	v_fmac_f32_e32 v214, v112, v7
	v_fmac_f32_e32 v215, v128, v7
	v_fmac_f32_e32 v214, v113, v8
	v_fmac_f32_e32 v215, v129, v8
	v_lshlrev_b32_e32 v5, 16, v154
	v_and_b32_e32 v6, 0xffff0000, v154
	v_fmac_f32_e32 v216, v112, v5
	v_fmac_f32_e32 v217, v128, v5
	v_fmac_f32_e32 v216, v113, v6
	v_fmac_f32_e32 v217, v129, v6
	v_lshlrev_b32_e32 v7, 16, v162
	v_and_b32_e32 v8, 0xffff0000, v162
	v_fmac_f32_e32 v218, v112, v7
	v_fmac_f32_e32 v219, v128, v7
	v_fmac_f32_e32 v218, v113, v8
	v_fmac_f32_e32 v219, v129, v8
	v_lshlrev_b32_e32 v5, 16, v170
	v_and_b32_e32 v6, 0xffff0000, v170
	v_fmac_f32_e32 v220, v112, v5
	v_fmac_f32_e32 v221, v128, v5
	v_fmac_f32_e32 v220, v113, v6
	v_fmac_f32_e32 v221, v129, v6
	v_lshlrev_b32_e32 v7, 16, v178
	v_and_b32_e32 v8, 0xffff0000, v178
	v_fmac_f32_e32 v222, v112, v7
	v_fmac_f32_e32 v223, v128, v7
	v_fmac_f32_e32 v222, v113, v8
	v_fmac_f32_e32 v223, v129, v8
	v_lshlrev_b32_e32 v5, 16, v186
	v_and_b32_e32 v6, 0xffff0000, v186
	v_fmac_f32_e32 v224, v112, v5
	v_fmac_f32_e32 v225, v128, v5
	v_fmac_f32_e32 v224, v113, v6
	v_fmac_f32_e32 v225, v129, v6
	v_lshlrev_b32_e32 v7, 16, v194
	v_and_b32_e32 v8, 0xffff0000, v194
	v_fmac_f32_e32 v226, v112, v7
	v_fmac_f32_e32 v227, v128, v7
	v_fmac_f32_e32 v226, v113, v8
	v_fmac_f32_e32 v227, v129, v8
	v_lshlrev_b32_e32 v5, 16, v202
	v_and_b32_e32 v6, 0xffff0000, v202
	v_fmac_f32_e32 v228, v112, v5
	v_fmac_f32_e32 v229, v128, v5
	v_fmac_f32_e32 v228, v113, v6
	v_fmac_f32_e32 v229, v129, v6
	v_lshlrev_b32_e32 v5, 16, v139
	v_and_b32_e32 v6, 0xffff0000, v139
	v_fmac_f32_e32 v212, v114, v5
	v_fmac_f32_e32 v213, v130, v5
	v_fmac_f32_e32 v212, v115, v6
	v_fmac_f32_e32 v213, v131, v6
	v_lshlrev_b32_e32 v7, 16, v147
	v_and_b32_e32 v8, 0xffff0000, v147
	v_fmac_f32_e32 v214, v114, v7
	v_fmac_f32_e32 v215, v130, v7
	v_fmac_f32_e32 v214, v115, v8
	v_fmac_f32_e32 v215, v131, v8
	v_lshlrev_b32_e32 v5, 16, v155
	v_and_b32_e32 v6, 0xffff0000, v155
	v_fmac_f32_e32 v216, v114, v5
	v_fmac_f32_e32 v217, v130, v5
	v_fmac_f32_e32 v216, v115, v6
	v_fmac_f32_e32 v217, v131, v6
	v_lshlrev_b32_e32 v7, 16, v163
	v_and_b32_e32 v8, 0xffff0000, v163
	v_fmac_f32_e32 v218, v114, v7
	v_fmac_f32_e32 v219, v130, v7
	v_fmac_f32_e32 v218, v115, v8
	v_fmac_f32_e32 v219, v131, v8
	v_lshlrev_b32_e32 v5, 16, v171
	v_and_b32_e32 v6, 0xffff0000, v171
	v_fmac_f32_e32 v220, v114, v5
	v_fmac_f32_e32 v221, v130, v5
	v_fmac_f32_e32 v220, v115, v6
	v_fmac_f32_e32 v221, v131, v6
	v_lshlrev_b32_e32 v7, 16, v179
	v_and_b32_e32 v8, 0xffff0000, v179
	v_fmac_f32_e32 v222, v114, v7
	v_fmac_f32_e32 v223, v130, v7
	v_fmac_f32_e32 v222, v115, v8
	v_fmac_f32_e32 v223, v131, v8
	v_lshlrev_b32_e32 v5, 16, v187
	v_and_b32_e32 v6, 0xffff0000, v187
	v_fmac_f32_e32 v224, v114, v5
	v_fmac_f32_e32 v225, v130, v5
	v_fmac_f32_e32 v224, v115, v6
	v_fmac_f32_e32 v225, v131, v6
	v_lshlrev_b32_e32 v7, 16, v195
	v_and_b32_e32 v8, 0xffff0000, v195
	v_fmac_f32_e32 v226, v114, v7
	v_fmac_f32_e32 v227, v130, v7
	v_fmac_f32_e32 v226, v115, v8
	v_fmac_f32_e32 v227, v131, v8
	v_lshlrev_b32_e32 v5, 16, v203
	v_and_b32_e32 v6, 0xffff0000, v203
	v_fmac_f32_e32 v228, v114, v5
	v_fmac_f32_e32 v229, v130, v5
	v_fmac_f32_e32 v228, v115, v6
	v_fmac_f32_e32 v229, v131, v6
	s_lshl_b32 s8, s5, 11
	s_add_u32 s28, s0, s8
	s_addc_u32 s29, s1, 0
	s_add_u32 s28, s28, 0x2100000
	s_addc_u32 s29, s29, 0
	global_load_dwordx4 v[132:135], v1, s[28:29]
	global_load_dwordx4 v[136:139], v1, s[28:29] offset:16
	s_add_u32 s28, s28, 0x80000
	s_addc_u32 s29, s29, 0
	global_load_dwordx4 v[140:143], v1, s[28:29]
	global_load_dwordx4 v[144:147], v1, s[28:29] offset:16
	s_add_u32 s28, s28, 0x80000
	s_addc_u32 s29, s29, 0
	global_load_dwordx4 v[148:151], v1, s[28:29]
	global_load_dwordx4 v[152:155], v1, s[28:29] offset:16
	s_add_u32 s28, s28, 0x80000
	s_addc_u32 s29, s29, 0
	global_load_dwordx4 v[156:159], v1, s[28:29]
	global_load_dwordx4 v[160:163], v1, s[28:29] offset:16
	s_add_u32 s28, s28, 0x80000
	s_addc_u32 s29, s29, 0
	global_load_dwordx4 v[164:167], v1, s[28:29]
	global_load_dwordx4 v[168:171], v1, s[28:29] offset:16
	s_add_u32 s28, s28, 0x80000
	s_addc_u32 s29, s29, 0
	global_load_dwordx4 v[172:175], v1, s[28:29]
	global_load_dwordx4 v[176:179], v1, s[28:29] offset:16
	s_add_u32 s28, s28, 0x80000
	s_addc_u32 s29, s29, 0
	global_load_dwordx4 v[180:183], v1, s[28:29]
	global_load_dwordx4 v[184:187], v1, s[28:29] offset:16
	s_add_u32 s28, s28, 0x80000
	s_addc_u32 s29, s29, 0
	global_load_dwordx4 v[188:191], v1, s[28:29]
	global_load_dwordx4 v[192:195], v1, s[28:29] offset:16
	s_add_u32 s28, s28, 0x80000
	s_addc_u32 s29, s29, 0
	global_load_dwordx4 v[196:199], v1, s[28:29]
	global_load_dwordx4 v[200:203], v1, s[28:29] offset:16
	s_add_u32 s28, s28, 0x80000
	s_addc_u32 s29, s29, 0
	v_add_f32_dpp v212, v212, v212 quad_perm:[1,0,3,2] row_mask:0xf bank_mask:0xf
	v_add_f32_dpp v213, v213, v213 quad_perm:[1,0,3,2] row_mask:0xf bank_mask:0xf
	v_add_f32_dpp v214, v214, v214 quad_perm:[1,0,3,2] row_mask:0xf bank_mask:0xf
	v_add_f32_dpp v215, v215, v215 quad_perm:[1,0,3,2] row_mask:0xf bank_mask:0xf
	v_add_f32_dpp v216, v216, v216 quad_perm:[1,0,3,2] row_mask:0xf bank_mask:0xf
	v_add_f32_dpp v217, v217, v217 quad_perm:[1,0,3,2] row_mask:0xf bank_mask:0xf
	v_add_f32_dpp v218, v218, v218 quad_perm:[1,0,3,2] row_mask:0xf bank_mask:0xf
	v_add_f32_dpp v219, v219, v219 quad_perm:[1,0,3,2] row_mask:0xf bank_mask:0xf
	v_add_f32_dpp v220, v220, v220 quad_perm:[1,0,3,2] row_mask:0xf bank_mask:0xf
	v_add_f32_dpp v221, v221, v221 quad_perm:[1,0,3,2] row_mask:0xf bank_mask:0xf
	v_add_f32_dpp v222, v222, v222 quad_perm:[1,0,3,2] row_mask:0xf bank_mask:0xf
	v_add_f32_dpp v223, v223, v223 quad_perm:[1,0,3,2] row_mask:0xf bank_mask:0xf
	v_add_f32_dpp v224, v224, v224 quad_perm:[1,0,3,2] row_mask:0xf bank_mask:0xf
	v_add_f32_dpp v225, v225, v225 quad_perm:[1,0,3,2] row_mask:0xf bank_mask:0xf
	v_add_f32_dpp v226, v226, v226 quad_perm:[1,0,3,2] row_mask:0xf bank_mask:0xf
	v_add_f32_dpp v227, v227, v227 quad_perm:[1,0,3,2] row_mask:0xf bank_mask:0xf
	v_add_f32_dpp v228, v228, v228 quad_perm:[1,0,3,2] row_mask:0xf bank_mask:0xf
	v_add_f32_dpp v229, v229, v229 quad_perm:[1,0,3,2] row_mask:0xf bank_mask:0xf
	v_add_f32_dpp v212, v212, v212 quad_perm:[2,3,0,1] row_mask:0xf bank_mask:0xf
	v_add_f32_dpp v213, v213, v213 quad_perm:[2,3,0,1] row_mask:0xf bank_mask:0xf
	v_add_f32_dpp v214, v214, v214 quad_perm:[2,3,0,1] row_mask:0xf bank_mask:0xf
	v_add_f32_dpp v215, v215, v215 quad_perm:[2,3,0,1] row_mask:0xf bank_mask:0xf
	v_add_f32_dpp v216, v216, v216 quad_perm:[2,3,0,1] row_mask:0xf bank_mask:0xf
	v_add_f32_dpp v217, v217, v217 quad_perm:[2,3,0,1] row_mask:0xf bank_mask:0xf
	v_add_f32_dpp v218, v218, v218 quad_perm:[2,3,0,1] row_mask:0xf bank_mask:0xf
	v_add_f32_dpp v219, v219, v219 quad_perm:[2,3,0,1] row_mask:0xf bank_mask:0xf
	v_add_f32_dpp v220, v220, v220 quad_perm:[2,3,0,1] row_mask:0xf bank_mask:0xf
	v_add_f32_dpp v221, v221, v221 quad_perm:[2,3,0,1] row_mask:0xf bank_mask:0xf
	v_add_f32_dpp v222, v222, v222 quad_perm:[2,3,0,1] row_mask:0xf bank_mask:0xf
	v_add_f32_dpp v223, v223, v223 quad_perm:[2,3,0,1] row_mask:0xf bank_mask:0xf
	v_add_f32_dpp v224, v224, v224 quad_perm:[2,3,0,1] row_mask:0xf bank_mask:0xf
	v_add_f32_dpp v225, v225, v225 quad_perm:[2,3,0,1] row_mask:0xf bank_mask:0xf
	v_add_f32_dpp v226, v226, v226 quad_perm:[2,3,0,1] row_mask:0xf bank_mask:0xf
	v_add_f32_dpp v227, v227, v227 quad_perm:[2,3,0,1] row_mask:0xf bank_mask:0xf
	v_add_f32_dpp v228, v228, v228 quad_perm:[2,3,0,1] row_mask:0xf bank_mask:0xf
	v_add_f32_dpp v229, v229, v229 quad_perm:[2,3,0,1] row_mask:0xf bank_mask:0xf
	v_add_f32_dpp v212, v212, v212 row_half_mirror row_mask:0xf bank_mask:0xf
	v_add_f32_dpp v213, v213, v213 row_half_mirror row_mask:0xf bank_mask:0xf
	v_add_f32_dpp v214, v214, v214 row_half_mirror row_mask:0xf bank_mask:0xf
	v_add_f32_dpp v215, v215, v215 row_half_mirror row_mask:0xf bank_mask:0xf
	v_add_f32_dpp v216, v216, v216 row_half_mirror row_mask:0xf bank_mask:0xf
	v_add_f32_dpp v217, v217, v217 row_half_mirror row_mask:0xf bank_mask:0xf
	v_add_f32_dpp v218, v218, v218 row_half_mirror row_mask:0xf bank_mask:0xf
	v_add_f32_dpp v219, v219, v219 row_half_mirror row_mask:0xf bank_mask:0xf
	v_add_f32_dpp v220, v220, v220 row_half_mirror row_mask:0xf bank_mask:0xf
	v_add_f32_dpp v221, v221, v221 row_half_mirror row_mask:0xf bank_mask:0xf
	v_add_f32_dpp v222, v222, v222 row_half_mirror row_mask:0xf bank_mask:0xf
	v_add_f32_dpp v223, v223, v223 row_half_mirror row_mask:0xf bank_mask:0xf
	v_add_f32_dpp v224, v224, v224 row_half_mirror row_mask:0xf bank_mask:0xf
	v_add_f32_dpp v225, v225, v225 row_half_mirror row_mask:0xf bank_mask:0xf
	v_add_f32_dpp v226, v226, v226 row_half_mirror row_mask:0xf bank_mask:0xf
	v_add_f32_dpp v227, v227, v227 row_half_mirror row_mask:0xf bank_mask:0xf
	v_add_f32_dpp v228, v228, v228 row_half_mirror row_mask:0xf bank_mask:0xf
	v_add_f32_dpp v229, v229, v229 row_half_mirror row_mask:0xf bank_mask:0xf
	v_add_f32_dpp v212, v212, v212 row_mirror row_mask:0xf bank_mask:0xf
	v_add_f32_dpp v213, v213, v213 row_mirror row_mask:0xf bank_mask:0xf
	v_add_f32_dpp v214, v214, v214 row_mirror row_mask:0xf bank_mask:0xf
	v_add_f32_dpp v215, v215, v215 row_mirror row_mask:0xf bank_mask:0xf
	v_add_f32_dpp v216, v216, v216 row_mirror row_mask:0xf bank_mask:0xf
	v_add_f32_dpp v217, v217, v217 row_mirror row_mask:0xf bank_mask:0xf
	v_add_f32_dpp v218, v218, v218 row_mirror row_mask:0xf bank_mask:0xf
	v_add_f32_dpp v219, v219, v219 row_mirror row_mask:0xf bank_mask:0xf
	v_add_f32_dpp v220, v220, v220 row_mirror row_mask:0xf bank_mask:0xf
	v_add_f32_dpp v221, v221, v221 row_mirror row_mask:0xf bank_mask:0xf
	v_add_f32_dpp v222, v222, v222 row_mirror row_mask:0xf bank_mask:0xf
	v_add_f32_dpp v223, v223, v223 row_mirror row_mask:0xf bank_mask:0xf
	v_add_f32_dpp v224, v224, v224 row_mirror row_mask:0xf bank_mask:0xf
	v_add_f32_dpp v225, v225, v225 row_mirror row_mask:0xf bank_mask:0xf
	v_add_f32_dpp v226, v226, v226 row_mirror row_mask:0xf bank_mask:0xf
	v_add_f32_dpp v227, v227, v227 row_mirror row_mask:0xf bank_mask:0xf
	v_add_f32_dpp v228, v228, v228 row_mirror row_mask:0xf bank_mask:0xf
	v_add_f32_dpp v229, v229, v229 row_mirror row_mask:0xf bank_mask:0xf
	v_add_f32_dpp v212, v212, v212 row_bcast:15 row_mask:0xa bank_mask:0xf
	v_add_f32_dpp v213, v213, v213 row_bcast:15 row_mask:0xa bank_mask:0xf
	v_add_f32_dpp v214, v214, v214 row_bcast:15 row_mask:0xa bank_mask:0xf
	v_add_f32_dpp v215, v215, v215 row_bcast:15 row_mask:0xa bank_mask:0xf
	v_add_f32_dpp v216, v216, v216 row_bcast:15 row_mask:0xa bank_mask:0xf
	v_add_f32_dpp v217, v217, v217 row_bcast:15 row_mask:0xa bank_mask:0xf
	v_add_f32_dpp v218, v218, v218 row_bcast:15 row_mask:0xa bank_mask:0xf
	v_add_f32_dpp v219, v219, v219 row_bcast:15 row_mask:0xa bank_mask:0xf
	v_add_f32_dpp v220, v220, v220 row_bcast:15 row_mask:0xa bank_mask:0xf
	v_add_f32_dpp v221, v221, v221 row_bcast:15 row_mask:0xa bank_mask:0xf
	v_add_f32_dpp v222, v222, v222 row_bcast:15 row_mask:0xa bank_mask:0xf
	v_add_f32_dpp v223, v223, v223 row_bcast:15 row_mask:0xa bank_mask:0xf
	v_add_f32_dpp v224, v224, v224 row_bcast:15 row_mask:0xa bank_mask:0xf
	v_add_f32_dpp v225, v225, v225 row_bcast:15 row_mask:0xa bank_mask:0xf
	v_add_f32_dpp v226, v226, v226 row_bcast:15 row_mask:0xa bank_mask:0xf
	v_add_f32_dpp v227, v227, v227 row_bcast:15 row_mask:0xa bank_mask:0xf
	v_add_f32_dpp v228, v228, v228 row_bcast:15 row_mask:0xa bank_mask:0xf
	v_add_f32_dpp v229, v229, v229 row_bcast:15 row_mask:0xa bank_mask:0xf
	v_add_f32_dpp v212, v212, v212 row_bcast:31 row_mask:0xc bank_mask:0xf
	v_add_f32_dpp v213, v213, v213 row_bcast:31 row_mask:0xc bank_mask:0xf
	v_add_f32_dpp v214, v214, v214 row_bcast:31 row_mask:0xc bank_mask:0xf
	v_add_f32_dpp v215, v215, v215 row_bcast:31 row_mask:0xc bank_mask:0xf
	v_add_f32_dpp v216, v216, v216 row_bcast:31 row_mask:0xc bank_mask:0xf
	v_add_f32_dpp v217, v217, v217 row_bcast:31 row_mask:0xc bank_mask:0xf
	v_add_f32_dpp v218, v218, v218 row_bcast:31 row_mask:0xc bank_mask:0xf
	v_add_f32_dpp v219, v219, v219 row_bcast:31 row_mask:0xc bank_mask:0xf
	v_add_f32_dpp v220, v220, v220 row_bcast:31 row_mask:0xc bank_mask:0xf
	v_add_f32_dpp v221, v221, v221 row_bcast:31 row_mask:0xc bank_mask:0xf
	v_add_f32_dpp v222, v222, v222 row_bcast:31 row_mask:0xc bank_mask:0xf
	v_add_f32_dpp v223, v223, v223 row_bcast:31 row_mask:0xc bank_mask:0xf
	v_add_f32_dpp v224, v224, v224 row_bcast:31 row_mask:0xc bank_mask:0xf
	v_add_f32_dpp v225, v225, v225 row_bcast:31 row_mask:0xc bank_mask:0xf
	v_add_f32_dpp v226, v226, v226 row_bcast:31 row_mask:0xc bank_mask:0xf
	v_add_f32_dpp v227, v227, v227 row_bcast:31 row_mask:0xc bank_mask:0xf
	v_add_f32_dpp v228, v228, v228 row_bcast:31 row_mask:0xc bank_mask:0xf
	v_add_f32_dpp v229, v229, v229 row_bcast:31 row_mask:0xc bank_mask:0xf
	s_nop 0
	v_readlane_b32 s32, v212, 63
	v_readlane_b32 s33, v213, 63
	v_readlane_b32 s40, v214, 63
	v_readlane_b32 s41, v215, 63
	v_readlane_b32 s46, v216, 63
	v_readlane_b32 s47, v217, 63
	v_readlane_b32 s51, v218, 63
	v_readlane_b32 s57, v219, 63
	v_readlane_b32 s58, v220, 63
	v_readlane_b32 s59, v221, 63
	v_readlane_b32 s60, v222, 63
	v_readlane_b32 s61, v223, 63
	v_readlane_b32 s62, v224, 63
	v_readlane_b32 s63, v225, 63
	v_readlane_b32 s70, v226, 63
	v_readlane_b32 s71, v227, 63
	v_readlane_b32 s74, v228, 63
	v_readlane_b32 s75, v229, 63
	s_nop 1
	v_writelane_b32 v9, s32, 0
	v_writelane_b32 v9, s33, 1
	v_writelane_b32 v9, s40, 2
	v_writelane_b32 v9, s41, 3
	v_writelane_b32 v9, s46, 4
	v_writelane_b32 v9, s47, 5
	v_writelane_b32 v9, s51, 6
	v_writelane_b32 v9, s57, 7
	v_writelane_b32 v9, s58, 8
	v_writelane_b32 v9, s59, 9
	v_writelane_b32 v9, s60, 10
	v_writelane_b32 v9, s61, 11
	v_writelane_b32 v9, s62, 12
	v_writelane_b32 v9, s63, 13
	v_writelane_b32 v9, s70, 14
	v_writelane_b32 v9, s71, 15
	v_writelane_b32 v9, s74, 16
	v_writelane_b32 v9, s75, 17
	s_mul_i32 s91, s3, 4608
	s_add_i32 s91, s91, s5
	s_add_u32 s8, s0, 0x3d00000
	s_addc_u32 s9, s1, 0
	v_add_u32_e32 v15, s91, v13
	v_lshlrev_b32_e32 v15, 2, v15
	s_mov_b64 exec, 0x3ffff
	global_store_dword v15, v9, s[8:9]
	s_mov_b64 exec, -1
	s_waitcnt vmcnt(0)
	v_lshlrev_b32_e32 v5, 16, v132
	v_and_b32_e32 v6, 0xffff0000, v132
	v_mul_f32_e32 v212, v16, v5
	v_mul_f32_e32 v213, v32, v5
	v_fmac_f32_e32 v212, v17, v6
	v_fmac_f32_e32 v213, v33, v6
	v_lshlrev_b32_e32 v7, 16, v140
	v_and_b32_e32 v8, 0xffff0000, v140
	v_mul_f32_e32 v214, v16, v7
	v_mul_f32_e32 v215, v32, v7
	v_fmac_f32_e32 v214, v17, v8
	v_fmac_f32_e32 v215, v33, v8
	v_lshlrev_b32_e32 v5, 16, v148
	v_and_b32_e32 v6, 0xffff0000, v148
	v_mul_f32_e32 v216, v16, v5
	v_mul_f32_e32 v217, v32, v5
	v_fmac_f32_e32 v216, v17, v6
	v_fmac_f32_e32 v217, v33, v6
	v_lshlrev_b32_e32 v7, 16, v156
	v_and_b32_e32 v8, 0xffff0000, v156
	v_mul_f32_e32 v218, v16, v7
	v_mul_f32_e32 v219, v32, v7
	v_fmac_f32_e32 v218, v17, v8
	v_fmac_f32_e32 v219, v33, v8
	v_lshlrev_b32_e32 v5, 16, v164
	v_and_b32_e32 v6, 0xffff0000, v164
	v_mul_f32_e32 v220, v16, v5
	v_mul_f32_e32 v221, v32, v5
	v_fmac_f32_e32 v220, v17, v6
	v_fmac_f32_e32 v221, v33, v6
	v_lshlrev_b32_e32 v7, 16, v172
	v_and_b32_e32 v8, 0xffff0000, v172
	v_mul_f32_e32 v222, v16, v7
	v_mul_f32_e32 v223, v32, v7
	v_fmac_f32_e32 v222, v17, v8
	v_fmac_f32_e32 v223, v33, v8
	v_lshlrev_b32_e32 v5, 16, v180
	v_and_b32_e32 v6, 0xffff0000, v180
	v_mul_f32_e32 v224, v16, v5
	v_mul_f32_e32 v225, v32, v5
	v_fmac_f32_e32 v224, v17, v6
	v_fmac_f32_e32 v225, v33, v6
	v_lshlrev_b32_e32 v7, 16, v188
	v_and_b32_e32 v8, 0xffff0000, v188
	v_mul_f32_e32 v226, v16, v7
	v_mul_f32_e32 v227, v32, v7
	v_fmac_f32_e32 v226, v17, v8
	v_fmac_f32_e32 v227, v33, v8
	v_lshlrev_b32_e32 v5, 16, v196
	v_and_b32_e32 v6, 0xffff0000, v196
	v_mul_f32_e32 v228, v16, v5
	v_mul_f32_e32 v229, v32, v5
	v_fmac_f32_e32 v228, v17, v6
	v_fmac_f32_e32 v229, v33, v6
	v_lshlrev_b32_e32 v5, 16, v133
	v_and_b32_e32 v6, 0xffff0000, v133
	v_fmac_f32_e32 v212, v18, v5
	v_fmac_f32_e32 v213, v34, v5
	v_fmac_f32_e32 v212, v19, v6
	v_fmac_f32_e32 v213, v35, v6
	v_lshlrev_b32_e32 v7, 16, v141
	v_and_b32_e32 v8, 0xffff0000, v141
	v_fmac_f32_e32 v214, v18, v7
	v_fmac_f32_e32 v215, v34, v7
	v_fmac_f32_e32 v214, v19, v8
	v_fmac_f32_e32 v215, v35, v8
	v_lshlrev_b32_e32 v5, 16, v149
	v_and_b32_e32 v6, 0xffff0000, v149
	v_fmac_f32_e32 v216, v18, v5
	v_fmac_f32_e32 v217, v34, v5
	v_fmac_f32_e32 v216, v19, v6
	v_fmac_f32_e32 v217, v35, v6
	v_lshlrev_b32_e32 v7, 16, v157
	v_and_b32_e32 v8, 0xffff0000, v157
	v_fmac_f32_e32 v218, v18, v7
	v_fmac_f32_e32 v219, v34, v7
	v_fmac_f32_e32 v218, v19, v8
	v_fmac_f32_e32 v219, v35, v8
	v_lshlrev_b32_e32 v5, 16, v165
	v_and_b32_e32 v6, 0xffff0000, v165
	v_fmac_f32_e32 v220, v18, v5
	v_fmac_f32_e32 v221, v34, v5
	v_fmac_f32_e32 v220, v19, v6
	v_fmac_f32_e32 v221, v35, v6
	v_lshlrev_b32_e32 v7, 16, v173
	v_and_b32_e32 v8, 0xffff0000, v173
	v_fmac_f32_e32 v222, v18, v7
	v_fmac_f32_e32 v223, v34, v7
	v_fmac_f32_e32 v222, v19, v8
	v_fmac_f32_e32 v223, v35, v8
	v_lshlrev_b32_e32 v5, 16, v181
	v_and_b32_e32 v6, 0xffff0000, v181
	v_fmac_f32_e32 v224, v18, v5
	v_fmac_f32_e32 v225, v34, v5
	v_fmac_f32_e32 v224, v19, v6
	v_fmac_f32_e32 v225, v35, v6
	v_lshlrev_b32_e32 v7, 16, v189
	v_and_b32_e32 v8, 0xffff0000, v189
	v_fmac_f32_e32 v226, v18, v7
	v_fmac_f32_e32 v227, v34, v7
	v_fmac_f32_e32 v226, v19, v8
	v_fmac_f32_e32 v227, v35, v8
	v_lshlrev_b32_e32 v5, 16, v197
	v_and_b32_e32 v6, 0xffff0000, v197
	v_fmac_f32_e32 v228, v18, v5
	v_fmac_f32_e32 v229, v34, v5
	v_fmac_f32_e32 v228, v19, v6
	v_fmac_f32_e32 v229, v35, v6
	v_lshlrev_b32_e32 v5, 16, v134
	v_and_b32_e32 v6, 0xffff0000, v134
	v_fmac_f32_e32 v212, v20, v5
	v_fmac_f32_e32 v213, v36, v5
	v_fmac_f32_e32 v212, v21, v6
	v_fmac_f32_e32 v213, v37, v6
	v_lshlrev_b32_e32 v7, 16, v142
	v_and_b32_e32 v8, 0xffff0000, v142
	v_fmac_f32_e32 v214, v20, v7
	v_fmac_f32_e32 v215, v36, v7
	v_fmac_f32_e32 v214, v21, v8
	v_fmac_f32_e32 v215, v37, v8
	v_lshlrev_b32_e32 v5, 16, v150
	v_and_b32_e32 v6, 0xffff0000, v150
	v_fmac_f32_e32 v216, v20, v5
	v_fmac_f32_e32 v217, v36, v5
	v_fmac_f32_e32 v216, v21, v6
	v_fmac_f32_e32 v217, v37, v6
	v_lshlrev_b32_e32 v7, 16, v158
	v_and_b32_e32 v8, 0xffff0000, v158
	v_fmac_f32_e32 v218, v20, v7
	v_fmac_f32_e32 v219, v36, v7
	v_fmac_f32_e32 v218, v21, v8
	v_fmac_f32_e32 v219, v37, v8
	v_lshlrev_b32_e32 v5, 16, v166
	v_and_b32_e32 v6, 0xffff0000, v166
	v_fmac_f32_e32 v220, v20, v5
	v_fmac_f32_e32 v221, v36, v5
	v_fmac_f32_e32 v220, v21, v6
	v_fmac_f32_e32 v221, v37, v6
	v_lshlrev_b32_e32 v7, 16, v174
	v_and_b32_e32 v8, 0xffff0000, v174
	v_fmac_f32_e32 v222, v20, v7
	v_fmac_f32_e32 v223, v36, v7
	v_fmac_f32_e32 v222, v21, v8
	v_fmac_f32_e32 v223, v37, v8
	v_lshlrev_b32_e32 v5, 16, v182
	v_and_b32_e32 v6, 0xffff0000, v182
	v_fmac_f32_e32 v224, v20, v5
	v_fmac_f32_e32 v225, v36, v5
	v_fmac_f32_e32 v224, v21, v6
	v_fmac_f32_e32 v225, v37, v6
	v_lshlrev_b32_e32 v7, 16, v190
	v_and_b32_e32 v8, 0xffff0000, v190
	v_fmac_f32_e32 v226, v20, v7
	v_fmac_f32_e32 v227, v36, v7
	v_fmac_f32_e32 v226, v21, v8
	v_fmac_f32_e32 v227, v37, v8
	v_lshlrev_b32_e32 v5, 16, v198
	v_and_b32_e32 v6, 0xffff0000, v198
	v_fmac_f32_e32 v228, v20, v5
	v_fmac_f32_e32 v229, v36, v5
	v_fmac_f32_e32 v228, v21, v6
	v_fmac_f32_e32 v229, v37, v6
	v_lshlrev_b32_e32 v5, 16, v135
	v_and_b32_e32 v6, 0xffff0000, v135
	v_fmac_f32_e32 v212, v22, v5
	v_fmac_f32_e32 v213, v38, v5
	v_fmac_f32_e32 v212, v23, v6
	v_fmac_f32_e32 v213, v39, v6
	v_lshlrev_b32_e32 v7, 16, v143
	v_and_b32_e32 v8, 0xffff0000, v143
	v_fmac_f32_e32 v214, v22, v7
	v_fmac_f32_e32 v215, v38, v7
	v_fmac_f32_e32 v214, v23, v8
	v_fmac_f32_e32 v215, v39, v8
	v_lshlrev_b32_e32 v5, 16, v151
	v_and_b32_e32 v6, 0xffff0000, v151
	v_fmac_f32_e32 v216, v22, v5
	v_fmac_f32_e32 v217, v38, v5
	v_fmac_f32_e32 v216, v23, v6
	v_fmac_f32_e32 v217, v39, v6
	v_lshlrev_b32_e32 v7, 16, v159
	v_and_b32_e32 v8, 0xffff0000, v159
	v_fmac_f32_e32 v218, v22, v7
	v_fmac_f32_e32 v219, v38, v7
	v_fmac_f32_e32 v218, v23, v8
	v_fmac_f32_e32 v219, v39, v8
	v_lshlrev_b32_e32 v5, 16, v167
	v_and_b32_e32 v6, 0xffff0000, v167
	v_fmac_f32_e32 v220, v22, v5
	v_fmac_f32_e32 v221, v38, v5
	v_fmac_f32_e32 v220, v23, v6
	v_fmac_f32_e32 v221, v39, v6
	v_lshlrev_b32_e32 v7, 16, v175
	v_and_b32_e32 v8, 0xffff0000, v175
	v_fmac_f32_e32 v222, v22, v7
	v_fmac_f32_e32 v223, v38, v7
	v_fmac_f32_e32 v222, v23, v8
	v_fmac_f32_e32 v223, v39, v8
	v_lshlrev_b32_e32 v5, 16, v183
	v_and_b32_e32 v6, 0xffff0000, v183
	v_fmac_f32_e32 v224, v22, v5
	v_fmac_f32_e32 v225, v38, v5
	v_fmac_f32_e32 v224, v23, v6
	v_fmac_f32_e32 v225, v39, v6
	v_lshlrev_b32_e32 v7, 16, v191
	v_and_b32_e32 v8, 0xffff0000, v191
	v_fmac_f32_e32 v226, v22, v7
	v_fmac_f32_e32 v227, v38, v7
	v_fmac_f32_e32 v226, v23, v8
	v_fmac_f32_e32 v227, v39, v8
	v_lshlrev_b32_e32 v5, 16, v199
	v_and_b32_e32 v6, 0xffff0000, v199
	v_fmac_f32_e32 v228, v22, v5
	v_fmac_f32_e32 v229, v38, v5
	v_fmac_f32_e32 v228, v23, v6
	v_fmac_f32_e32 v229, v39, v6
	v_lshlrev_b32_e32 v5, 16, v136
	v_and_b32_e32 v6, 0xffff0000, v136
	v_fmac_f32_e32 v212, v24, v5
	v_fmac_f32_e32 v213, v40, v5
	v_fmac_f32_e32 v212, v25, v6
	v_fmac_f32_e32 v213, v41, v6
	v_lshlrev_b32_e32 v7, 16, v144
	v_and_b32_e32 v8, 0xffff0000, v144
	v_fmac_f32_e32 v214, v24, v7
	v_fmac_f32_e32 v215, v40, v7
	v_fmac_f32_e32 v214, v25, v8
	v_fmac_f32_e32 v215, v41, v8
	v_lshlrev_b32_e32 v5, 16, v152
	v_and_b32_e32 v6, 0xffff0000, v152
	v_fmac_f32_e32 v216, v24, v5
	v_fmac_f32_e32 v217, v40, v5
	v_fmac_f32_e32 v216, v25, v6
	v_fmac_f32_e32 v217, v41, v6
	v_lshlrev_b32_e32 v7, 16, v160
	v_and_b32_e32 v8, 0xffff0000, v160
	v_fmac_f32_e32 v218, v24, v7
	v_fmac_f32_e32 v219, v40, v7
	v_fmac_f32_e32 v218, v25, v8
	v_fmac_f32_e32 v219, v41, v8
	v_lshlrev_b32_e32 v5, 16, v168
	v_and_b32_e32 v6, 0xffff0000, v168
	v_fmac_f32_e32 v220, v24, v5
	v_fmac_f32_e32 v221, v40, v5
	v_fmac_f32_e32 v220, v25, v6
	v_fmac_f32_e32 v221, v41, v6
	v_lshlrev_b32_e32 v7, 16, v176
	v_and_b32_e32 v8, 0xffff0000, v176
	v_fmac_f32_e32 v222, v24, v7
	v_fmac_f32_e32 v223, v40, v7
	v_fmac_f32_e32 v222, v25, v8
	v_fmac_f32_e32 v223, v41, v8
	v_lshlrev_b32_e32 v5, 16, v184
	v_and_b32_e32 v6, 0xffff0000, v184
	v_fmac_f32_e32 v224, v24, v5
	v_fmac_f32_e32 v225, v40, v5
	v_fmac_f32_e32 v224, v25, v6
	v_fmac_f32_e32 v225, v41, v6
	v_lshlrev_b32_e32 v7, 16, v192
	v_and_b32_e32 v8, 0xffff0000, v192
	v_fmac_f32_e32 v226, v24, v7
	v_fmac_f32_e32 v227, v40, v7
	v_fmac_f32_e32 v226, v25, v8
	v_fmac_f32_e32 v227, v41, v8
	v_lshlrev_b32_e32 v5, 16, v200
	v_and_b32_e32 v6, 0xffff0000, v200
	v_fmac_f32_e32 v228, v24, v5
	v_fmac_f32_e32 v229, v40, v5
	v_fmac_f32_e32 v228, v25, v6
	v_fmac_f32_e32 v229, v41, v6
	v_lshlrev_b32_e32 v5, 16, v137
	v_and_b32_e32 v6, 0xffff0000, v137
	v_fmac_f32_e32 v212, v26, v5
	v_fmac_f32_e32 v213, v42, v5
	v_fmac_f32_e32 v212, v27, v6
	v_fmac_f32_e32 v213, v43, v6
	v_lshlrev_b32_e32 v7, 16, v145
	v_and_b32_e32 v8, 0xffff0000, v145
	v_fmac_f32_e32 v214, v26, v7
	v_fmac_f32_e32 v215, v42, v7
	v_fmac_f32_e32 v214, v27, v8
	v_fmac_f32_e32 v215, v43, v8
	v_lshlrev_b32_e32 v5, 16, v153
	v_and_b32_e32 v6, 0xffff0000, v153
	v_fmac_f32_e32 v216, v26, v5
	v_fmac_f32_e32 v217, v42, v5
	v_fmac_f32_e32 v216, v27, v6
	v_fmac_f32_e32 v217, v43, v6
	v_lshlrev_b32_e32 v7, 16, v161
	v_and_b32_e32 v8, 0xffff0000, v161
	v_fmac_f32_e32 v218, v26, v7
	v_fmac_f32_e32 v219, v42, v7
	v_fmac_f32_e32 v218, v27, v8
	v_fmac_f32_e32 v219, v43, v8
	v_lshlrev_b32_e32 v5, 16, v169
	v_and_b32_e32 v6, 0xffff0000, v169
	v_fmac_f32_e32 v220, v26, v5
	v_fmac_f32_e32 v221, v42, v5
	v_fmac_f32_e32 v220, v27, v6
	v_fmac_f32_e32 v221, v43, v6
	v_lshlrev_b32_e32 v7, 16, v177
	v_and_b32_e32 v8, 0xffff0000, v177
	v_fmac_f32_e32 v222, v26, v7
	v_fmac_f32_e32 v223, v42, v7
	v_fmac_f32_e32 v222, v27, v8
	v_fmac_f32_e32 v223, v43, v8
	v_lshlrev_b32_e32 v5, 16, v185
	v_and_b32_e32 v6, 0xffff0000, v185
	v_fmac_f32_e32 v224, v26, v5
	v_fmac_f32_e32 v225, v42, v5
	v_fmac_f32_e32 v224, v27, v6
	v_fmac_f32_e32 v225, v43, v6
	v_lshlrev_b32_e32 v7, 16, v193
	v_and_b32_e32 v8, 0xffff0000, v193
	v_fmac_f32_e32 v226, v26, v7
	v_fmac_f32_e32 v227, v42, v7
	v_fmac_f32_e32 v226, v27, v8
	v_fmac_f32_e32 v227, v43, v8
	v_lshlrev_b32_e32 v5, 16, v201
	v_and_b32_e32 v6, 0xffff0000, v201
	v_fmac_f32_e32 v228, v26, v5
	v_fmac_f32_e32 v229, v42, v5
	v_fmac_f32_e32 v228, v27, v6
	v_fmac_f32_e32 v229, v43, v6
	v_lshlrev_b32_e32 v5, 16, v138
	v_and_b32_e32 v6, 0xffff0000, v138
	v_fmac_f32_e32 v212, v28, v5
	v_fmac_f32_e32 v213, v44, v5
	v_fmac_f32_e32 v212, v29, v6
	v_fmac_f32_e32 v213, v45, v6
	v_lshlrev_b32_e32 v7, 16, v146
	v_and_b32_e32 v8, 0xffff0000, v146
	v_fmac_f32_e32 v214, v28, v7
	v_fmac_f32_e32 v215, v44, v7
	v_fmac_f32_e32 v214, v29, v8
	v_fmac_f32_e32 v215, v45, v8
	v_lshlrev_b32_e32 v5, 16, v154
	v_and_b32_e32 v6, 0xffff0000, v154
	v_fmac_f32_e32 v216, v28, v5
	v_fmac_f32_e32 v217, v44, v5
	v_fmac_f32_e32 v216, v29, v6
	v_fmac_f32_e32 v217, v45, v6
	v_lshlrev_b32_e32 v7, 16, v162
	v_and_b32_e32 v8, 0xffff0000, v162
	v_fmac_f32_e32 v218, v28, v7
	v_fmac_f32_e32 v219, v44, v7
	v_fmac_f32_e32 v218, v29, v8
	v_fmac_f32_e32 v219, v45, v8
	v_lshlrev_b32_e32 v5, 16, v170
	v_and_b32_e32 v6, 0xffff0000, v170
	v_fmac_f32_e32 v220, v28, v5
	v_fmac_f32_e32 v221, v44, v5
	v_fmac_f32_e32 v220, v29, v6
	v_fmac_f32_e32 v221, v45, v6
	v_lshlrev_b32_e32 v7, 16, v178
	v_and_b32_e32 v8, 0xffff0000, v178
	v_fmac_f32_e32 v222, v28, v7
	v_fmac_f32_e32 v223, v44, v7
	v_fmac_f32_e32 v222, v29, v8
	v_fmac_f32_e32 v223, v45, v8
	v_lshlrev_b32_e32 v5, 16, v186
	v_and_b32_e32 v6, 0xffff0000, v186
	v_fmac_f32_e32 v224, v28, v5
	v_fmac_f32_e32 v225, v44, v5
	v_fmac_f32_e32 v224, v29, v6
	v_fmac_f32_e32 v225, v45, v6
	v_lshlrev_b32_e32 v7, 16, v194
	v_and_b32_e32 v8, 0xffff0000, v194
	v_fmac_f32_e32 v226, v28, v7
	v_fmac_f32_e32 v227, v44, v7
	v_fmac_f32_e32 v226, v29, v8
	v_fmac_f32_e32 v227, v45, v8
	v_lshlrev_b32_e32 v5, 16, v202
	v_and_b32_e32 v6, 0xffff0000, v202
	v_fmac_f32_e32 v228, v28, v5
	v_fmac_f32_e32 v229, v44, v5
	v_fmac_f32_e32 v228, v29, v6
	v_fmac_f32_e32 v229, v45, v6
	v_lshlrev_b32_e32 v5, 16, v139
	v_and_b32_e32 v6, 0xffff0000, v139
	v_fmac_f32_e32 v212, v30, v5
	v_fmac_f32_e32 v213, v46, v5
	v_fmac_f32_e32 v212, v31, v6
	v_fmac_f32_e32 v213, v47, v6
	v_lshlrev_b32_e32 v7, 16, v147
	v_and_b32_e32 v8, 0xffff0000, v147
	v_fmac_f32_e32 v214, v30, v7
	v_fmac_f32_e32 v215, v46, v7
	v_fmac_f32_e32 v214, v31, v8
	v_fmac_f32_e32 v215, v47, v8
	v_lshlrev_b32_e32 v5, 16, v155
	v_and_b32_e32 v6, 0xffff0000, v155
	v_fmac_f32_e32 v216, v30, v5
	v_fmac_f32_e32 v217, v46, v5
	v_fmac_f32_e32 v216, v31, v6
	v_fmac_f32_e32 v217, v47, v6
	v_lshlrev_b32_e32 v7, 16, v163
	v_and_b32_e32 v8, 0xffff0000, v163
	v_fmac_f32_e32 v218, v30, v7
	v_fmac_f32_e32 v219, v46, v7
	v_fmac_f32_e32 v218, v31, v8
	v_fmac_f32_e32 v219, v47, v8
	v_lshlrev_b32_e32 v5, 16, v171
	v_and_b32_e32 v6, 0xffff0000, v171
	v_fmac_f32_e32 v220, v30, v5
	v_fmac_f32_e32 v221, v46, v5
	v_fmac_f32_e32 v220, v31, v6
	v_fmac_f32_e32 v221, v47, v6
	v_lshlrev_b32_e32 v7, 16, v179
	v_and_b32_e32 v8, 0xffff0000, v179
	v_fmac_f32_e32 v222, v30, v7
	v_fmac_f32_e32 v223, v46, v7
	v_fmac_f32_e32 v222, v31, v8
	v_fmac_f32_e32 v223, v47, v8
	v_lshlrev_b32_e32 v5, 16, v187
	v_and_b32_e32 v6, 0xffff0000, v187
	v_fmac_f32_e32 v224, v30, v5
	v_fmac_f32_e32 v225, v46, v5
	v_fmac_f32_e32 v224, v31, v6
	v_fmac_f32_e32 v225, v47, v6
	v_lshlrev_b32_e32 v7, 16, v195
	v_and_b32_e32 v8, 0xffff0000, v195
	v_fmac_f32_e32 v226, v30, v7
	v_fmac_f32_e32 v227, v46, v7
	v_fmac_f32_e32 v226, v31, v8
	v_fmac_f32_e32 v227, v47, v8
	v_lshlrev_b32_e32 v5, 16, v203
	v_and_b32_e32 v6, 0xffff0000, v203
	v_fmac_f32_e32 v228, v30, v5
	v_fmac_f32_e32 v229, v46, v5
	v_fmac_f32_e32 v228, v31, v6
	v_fmac_f32_e32 v229, v47, v6
	global_load_dwordx4 v[132:135], v1, s[28:29]
	global_load_dwordx4 v[136:139], v1, s[28:29] offset:16
	s_add_u32 s28, s28, 0x80000
	s_addc_u32 s29, s29, 0
	global_load_dwordx4 v[140:143], v1, s[28:29]
	global_load_dwordx4 v[144:147], v1, s[28:29] offset:16
	s_add_u32 s28, s28, 0x80000
	s_addc_u32 s29, s29, 0
	global_load_dwordx4 v[148:151], v1, s[28:29]
	global_load_dwordx4 v[152:155], v1, s[28:29] offset:16
	s_add_u32 s28, s28, 0x80000
	s_addc_u32 s29, s29, 0
	global_load_dwordx4 v[156:159], v1, s[28:29]
	global_load_dwordx4 v[160:163], v1, s[28:29] offset:16
	s_add_u32 s28, s28, 0x80000
	s_addc_u32 s29, s29, 0
	global_load_dwordx4 v[164:167], v1, s[28:29]
	global_load_dwordx4 v[168:171], v1, s[28:29] offset:16
	s_add_u32 s28, s28, 0x80000
	s_addc_u32 s29, s29, 0
	global_load_dwordx4 v[172:175], v1, s[28:29]
	global_load_dwordx4 v[176:179], v1, s[28:29] offset:16
	s_add_u32 s28, s28, 0x80000
	s_addc_u32 s29, s29, 0
	global_load_dwordx4 v[180:183], v1, s[28:29]
	global_load_dwordx4 v[184:187], v1, s[28:29] offset:16
	s_add_u32 s28, s28, 0x80000
	s_addc_u32 s29, s29, 0
	global_load_dwordx4 v[188:191], v1, s[28:29]
	global_load_dwordx4 v[192:195], v1, s[28:29] offset:16
	s_add_u32 s28, s28, 0x80000
	s_addc_u32 s29, s29, 0
	global_load_dwordx4 v[196:199], v1, s[28:29]
	global_load_dwordx4 v[200:203], v1, s[28:29] offset:16
	s_add_u32 s28, s28, 0x80000
	s_addc_u32 s29, s29, 0
	v_add_f32_dpp v212, v212, v212 quad_perm:[1,0,3,2] row_mask:0xf bank_mask:0xf
	v_add_f32_dpp v213, v213, v213 quad_perm:[1,0,3,2] row_mask:0xf bank_mask:0xf
	v_add_f32_dpp v214, v214, v214 quad_perm:[1,0,3,2] row_mask:0xf bank_mask:0xf
	v_add_f32_dpp v215, v215, v215 quad_perm:[1,0,3,2] row_mask:0xf bank_mask:0xf
	v_add_f32_dpp v216, v216, v216 quad_perm:[1,0,3,2] row_mask:0xf bank_mask:0xf
	v_add_f32_dpp v217, v217, v217 quad_perm:[1,0,3,2] row_mask:0xf bank_mask:0xf
	v_add_f32_dpp v218, v218, v218 quad_perm:[1,0,3,2] row_mask:0xf bank_mask:0xf
	v_add_f32_dpp v219, v219, v219 quad_perm:[1,0,3,2] row_mask:0xf bank_mask:0xf
	v_add_f32_dpp v220, v220, v220 quad_perm:[1,0,3,2] row_mask:0xf bank_mask:0xf
	v_add_f32_dpp v221, v221, v221 quad_perm:[1,0,3,2] row_mask:0xf bank_mask:0xf
	v_add_f32_dpp v222, v222, v222 quad_perm:[1,0,3,2] row_mask:0xf bank_mask:0xf
	v_add_f32_dpp v223, v223, v223 quad_perm:[1,0,3,2] row_mask:0xf bank_mask:0xf
	v_add_f32_dpp v224, v224, v224 quad_perm:[1,0,3,2] row_mask:0xf bank_mask:0xf
	v_add_f32_dpp v225, v225, v225 quad_perm:[1,0,3,2] row_mask:0xf bank_mask:0xf
	v_add_f32_dpp v226, v226, v226 quad_perm:[1,0,3,2] row_mask:0xf bank_mask:0xf
	v_add_f32_dpp v227, v227, v227 quad_perm:[1,0,3,2] row_mask:0xf bank_mask:0xf
	v_add_f32_dpp v228, v228, v228 quad_perm:[1,0,3,2] row_mask:0xf bank_mask:0xf
	v_add_f32_dpp v229, v229, v229 quad_perm:[1,0,3,2] row_mask:0xf bank_mask:0xf
	v_add_f32_dpp v212, v212, v212 quad_perm:[2,3,0,1] row_mask:0xf bank_mask:0xf
	v_add_f32_dpp v213, v213, v213 quad_perm:[2,3,0,1] row_mask:0xf bank_mask:0xf
	v_add_f32_dpp v214, v214, v214 quad_perm:[2,3,0,1] row_mask:0xf bank_mask:0xf
	v_add_f32_dpp v215, v215, v215 quad_perm:[2,3,0,1] row_mask:0xf bank_mask:0xf
	v_add_f32_dpp v216, v216, v216 quad_perm:[2,3,0,1] row_mask:0xf bank_mask:0xf
	v_add_f32_dpp v217, v217, v217 quad_perm:[2,3,0,1] row_mask:0xf bank_mask:0xf
	v_add_f32_dpp v218, v218, v218 quad_perm:[2,3,0,1] row_mask:0xf bank_mask:0xf
	v_add_f32_dpp v219, v219, v219 quad_perm:[2,3,0,1] row_mask:0xf bank_mask:0xf
	v_add_f32_dpp v220, v220, v220 quad_perm:[2,3,0,1] row_mask:0xf bank_mask:0xf
	v_add_f32_dpp v221, v221, v221 quad_perm:[2,3,0,1] row_mask:0xf bank_mask:0xf
	v_add_f32_dpp v222, v222, v222 quad_perm:[2,3,0,1] row_mask:0xf bank_mask:0xf
	v_add_f32_dpp v223, v223, v223 quad_perm:[2,3,0,1] row_mask:0xf bank_mask:0xf
	v_add_f32_dpp v224, v224, v224 quad_perm:[2,3,0,1] row_mask:0xf bank_mask:0xf
	v_add_f32_dpp v225, v225, v225 quad_perm:[2,3,0,1] row_mask:0xf bank_mask:0xf
	v_add_f32_dpp v226, v226, v226 quad_perm:[2,3,0,1] row_mask:0xf bank_mask:0xf
	v_add_f32_dpp v227, v227, v227 quad_perm:[2,3,0,1] row_mask:0xf bank_mask:0xf
	v_add_f32_dpp v228, v228, v228 quad_perm:[2,3,0,1] row_mask:0xf bank_mask:0xf
	v_add_f32_dpp v229, v229, v229 quad_perm:[2,3,0,1] row_mask:0xf bank_mask:0xf
	v_add_f32_dpp v212, v212, v212 row_half_mirror row_mask:0xf bank_mask:0xf
	v_add_f32_dpp v213, v213, v213 row_half_mirror row_mask:0xf bank_mask:0xf
	v_add_f32_dpp v214, v214, v214 row_half_mirror row_mask:0xf bank_mask:0xf
	v_add_f32_dpp v215, v215, v215 row_half_mirror row_mask:0xf bank_mask:0xf
	v_add_f32_dpp v216, v216, v216 row_half_mirror row_mask:0xf bank_mask:0xf
	v_add_f32_dpp v217, v217, v217 row_half_mirror row_mask:0xf bank_mask:0xf
	v_add_f32_dpp v218, v218, v218 row_half_mirror row_mask:0xf bank_mask:0xf
	v_add_f32_dpp v219, v219, v219 row_half_mirror row_mask:0xf bank_mask:0xf
	v_add_f32_dpp v220, v220, v220 row_half_mirror row_mask:0xf bank_mask:0xf
	v_add_f32_dpp v221, v221, v221 row_half_mirror row_mask:0xf bank_mask:0xf
	v_add_f32_dpp v222, v222, v222 row_half_mirror row_mask:0xf bank_mask:0xf
	v_add_f32_dpp v223, v223, v223 row_half_mirror row_mask:0xf bank_mask:0xf
	v_add_f32_dpp v224, v224, v224 row_half_mirror row_mask:0xf bank_mask:0xf
	v_add_f32_dpp v225, v225, v225 row_half_mirror row_mask:0xf bank_mask:0xf
	v_add_f32_dpp v226, v226, v226 row_half_mirror row_mask:0xf bank_mask:0xf
	v_add_f32_dpp v227, v227, v227 row_half_mirror row_mask:0xf bank_mask:0xf
	v_add_f32_dpp v228, v228, v228 row_half_mirror row_mask:0xf bank_mask:0xf
	v_add_f32_dpp v229, v229, v229 row_half_mirror row_mask:0xf bank_mask:0xf
	v_add_f32_dpp v212, v212, v212 row_mirror row_mask:0xf bank_mask:0xf
	v_add_f32_dpp v213, v213, v213 row_mirror row_mask:0xf bank_mask:0xf
	v_add_f32_dpp v214, v214, v214 row_mirror row_mask:0xf bank_mask:0xf
	v_add_f32_dpp v215, v215, v215 row_mirror row_mask:0xf bank_mask:0xf
	v_add_f32_dpp v216, v216, v216 row_mirror row_mask:0xf bank_mask:0xf
	v_add_f32_dpp v217, v217, v217 row_mirror row_mask:0xf bank_mask:0xf
	v_add_f32_dpp v218, v218, v218 row_mirror row_mask:0xf bank_mask:0xf
	v_add_f32_dpp v219, v219, v219 row_mirror row_mask:0xf bank_mask:0xf
	v_add_f32_dpp v220, v220, v220 row_mirror row_mask:0xf bank_mask:0xf
	v_add_f32_dpp v221, v221, v221 row_mirror row_mask:0xf bank_mask:0xf
	v_add_f32_dpp v222, v222, v222 row_mirror row_mask:0xf bank_mask:0xf
	v_add_f32_dpp v223, v223, v223 row_mirror row_mask:0xf bank_mask:0xf
	v_add_f32_dpp v224, v224, v224 row_mirror row_mask:0xf bank_mask:0xf
	v_add_f32_dpp v225, v225, v225 row_mirror row_mask:0xf bank_mask:0xf
	v_add_f32_dpp v226, v226, v226 row_mirror row_mask:0xf bank_mask:0xf
	v_add_f32_dpp v227, v227, v227 row_mirror row_mask:0xf bank_mask:0xf
	v_add_f32_dpp v228, v228, v228 row_mirror row_mask:0xf bank_mask:0xf
	v_add_f32_dpp v229, v229, v229 row_mirror row_mask:0xf bank_mask:0xf
	v_add_f32_dpp v212, v212, v212 row_bcast:15 row_mask:0xa bank_mask:0xf
	v_add_f32_dpp v213, v213, v213 row_bcast:15 row_mask:0xa bank_mask:0xf
	v_add_f32_dpp v214, v214, v214 row_bcast:15 row_mask:0xa bank_mask:0xf
	v_add_f32_dpp v215, v215, v215 row_bcast:15 row_mask:0xa bank_mask:0xf
	v_add_f32_dpp v216, v216, v216 row_bcast:15 row_mask:0xa bank_mask:0xf
	v_add_f32_dpp v217, v217, v217 row_bcast:15 row_mask:0xa bank_mask:0xf
	v_add_f32_dpp v218, v218, v218 row_bcast:15 row_mask:0xa bank_mask:0xf
	v_add_f32_dpp v219, v219, v219 row_bcast:15 row_mask:0xa bank_mask:0xf
	v_add_f32_dpp v220, v220, v220 row_bcast:15 row_mask:0xa bank_mask:0xf
	v_add_f32_dpp v221, v221, v221 row_bcast:15 row_mask:0xa bank_mask:0xf
	v_add_f32_dpp v222, v222, v222 row_bcast:15 row_mask:0xa bank_mask:0xf
	v_add_f32_dpp v223, v223, v223 row_bcast:15 row_mask:0xa bank_mask:0xf
	v_add_f32_dpp v224, v224, v224 row_bcast:15 row_mask:0xa bank_mask:0xf
	v_add_f32_dpp v225, v225, v225 row_bcast:15 row_mask:0xa bank_mask:0xf
	v_add_f32_dpp v226, v226, v226 row_bcast:15 row_mask:0xa bank_mask:0xf
	v_add_f32_dpp v227, v227, v227 row_bcast:15 row_mask:0xa bank_mask:0xf
	v_add_f32_dpp v228, v228, v228 row_bcast:15 row_mask:0xa bank_mask:0xf
	v_add_f32_dpp v229, v229, v229 row_bcast:15 row_mask:0xa bank_mask:0xf
	v_add_f32_dpp v212, v212, v212 row_bcast:31 row_mask:0xc bank_mask:0xf
	v_add_f32_dpp v213, v213, v213 row_bcast:31 row_mask:0xc bank_mask:0xf
	v_add_f32_dpp v214, v214, v214 row_bcast:31 row_mask:0xc bank_mask:0xf
	v_add_f32_dpp v215, v215, v215 row_bcast:31 row_mask:0xc bank_mask:0xf
	v_add_f32_dpp v216, v216, v216 row_bcast:31 row_mask:0xc bank_mask:0xf
	v_add_f32_dpp v217, v217, v217 row_bcast:31 row_mask:0xc bank_mask:0xf
	v_add_f32_dpp v218, v218, v218 row_bcast:31 row_mask:0xc bank_mask:0xf
	v_add_f32_dpp v219, v219, v219 row_bcast:31 row_mask:0xc bank_mask:0xf
	v_add_f32_dpp v220, v220, v220 row_bcast:31 row_mask:0xc bank_mask:0xf
	v_add_f32_dpp v221, v221, v221 row_bcast:31 row_mask:0xc bank_mask:0xf
	v_add_f32_dpp v222, v222, v222 row_bcast:31 row_mask:0xc bank_mask:0xf
	v_add_f32_dpp v223, v223, v223 row_bcast:31 row_mask:0xc bank_mask:0xf
	v_add_f32_dpp v224, v224, v224 row_bcast:31 row_mask:0xc bank_mask:0xf
	v_add_f32_dpp v225, v225, v225 row_bcast:31 row_mask:0xc bank_mask:0xf
	v_add_f32_dpp v226, v226, v226 row_bcast:31 row_mask:0xc bank_mask:0xf
	v_add_f32_dpp v227, v227, v227 row_bcast:31 row_mask:0xc bank_mask:0xf
	v_add_f32_dpp v228, v228, v228 row_bcast:31 row_mask:0xc bank_mask:0xf
	v_add_f32_dpp v229, v229, v229 row_bcast:31 row_mask:0xc bank_mask:0xf
	s_nop 0
	v_readlane_b32 s32, v212, 63
	v_readlane_b32 s33, v213, 63
	v_readlane_b32 s40, v214, 63
	v_readlane_b32 s41, v215, 63
	v_readlane_b32 s46, v216, 63
	v_readlane_b32 s47, v217, 63
	v_readlane_b32 s51, v218, 63
	v_readlane_b32 s57, v219, 63
	v_readlane_b32 s58, v220, 63
	v_readlane_b32 s59, v221, 63
	v_readlane_b32 s60, v222, 63
	v_readlane_b32 s61, v223, 63
	v_readlane_b32 s62, v224, 63
	v_readlane_b32 s63, v225, 63
	v_readlane_b32 s70, v226, 63
	v_readlane_b32 s71, v227, 63
	v_readlane_b32 s74, v228, 63
	v_readlane_b32 s75, v229, 63
	s_nop 1
	v_writelane_b32 v9, s32, 0
	v_writelane_b32 v9, s33, 1
	v_writelane_b32 v9, s40, 2
	v_writelane_b32 v9, s41, 3
	v_writelane_b32 v9, s46, 4
	v_writelane_b32 v9, s47, 5
	v_writelane_b32 v9, s51, 6
	v_writelane_b32 v9, s57, 7
	v_writelane_b32 v9, s58, 8
	v_writelane_b32 v9, s59, 9
	v_writelane_b32 v9, s60, 10
	v_writelane_b32 v9, s61, 11
	v_writelane_b32 v9, s62, 12
	v_writelane_b32 v9, s63, 13
	v_writelane_b32 v9, s70, 14
	v_writelane_b32 v9, s71, 15
	v_writelane_b32 v9, s74, 16
	v_writelane_b32 v9, s75, 17
	s_mul_i32 s91, s3, 11264
	s_add_i32 s91, s91, s5
	s_add_u32 s8, s0, 0x3e00000
	s_addc_u32 s9, s1, 0
	v_add_u32_e32 v15, s91, v14
	v_lshlrev_b32_e32 v15, 2, v15
	s_mov_b64 exec, 0x3ffff
	global_store_dword v15, v9, s[8:9]
	s_mov_b64 exec, -1
	s_waitcnt vmcnt(0)
	v_lshlrev_b32_e32 v5, 16, v132
	v_and_b32_e32 v6, 0xffff0000, v132
	v_mul_f32_e32 v212, v16, v5
	v_mul_f32_e32 v213, v32, v5
	v_fmac_f32_e32 v212, v17, v6
	v_fmac_f32_e32 v213, v33, v6
	v_lshlrev_b32_e32 v7, 16, v140
	v_and_b32_e32 v8, 0xffff0000, v140
	v_mul_f32_e32 v214, v16, v7
	v_mul_f32_e32 v215, v32, v7
	v_fmac_f32_e32 v214, v17, v8
	v_fmac_f32_e32 v215, v33, v8
	v_lshlrev_b32_e32 v5, 16, v148
	v_and_b32_e32 v6, 0xffff0000, v148
	v_mul_f32_e32 v216, v16, v5
	v_mul_f32_e32 v217, v32, v5
	v_fmac_f32_e32 v216, v17, v6
	v_fmac_f32_e32 v217, v33, v6
	v_lshlrev_b32_e32 v7, 16, v156
	v_and_b32_e32 v8, 0xffff0000, v156
	v_mul_f32_e32 v218, v16, v7
	v_mul_f32_e32 v219, v32, v7
	v_fmac_f32_e32 v218, v17, v8
	v_fmac_f32_e32 v219, v33, v8
	v_lshlrev_b32_e32 v5, 16, v164
	v_and_b32_e32 v6, 0xffff0000, v164
	v_mul_f32_e32 v220, v16, v5
	v_mul_f32_e32 v221, v32, v5
	v_fmac_f32_e32 v220, v17, v6
	v_fmac_f32_e32 v221, v33, v6
	v_lshlrev_b32_e32 v7, 16, v172
	v_and_b32_e32 v8, 0xffff0000, v172
	v_mul_f32_e32 v222, v16, v7
	v_mul_f32_e32 v223, v32, v7
	v_fmac_f32_e32 v222, v17, v8
	v_fmac_f32_e32 v223, v33, v8
	v_lshlrev_b32_e32 v5, 16, v180
	v_and_b32_e32 v6, 0xffff0000, v180
	v_mul_f32_e32 v224, v16, v5
	v_mul_f32_e32 v225, v32, v5
	v_fmac_f32_e32 v224, v17, v6
	v_fmac_f32_e32 v225, v33, v6
	v_lshlrev_b32_e32 v7, 16, v188
	v_and_b32_e32 v8, 0xffff0000, v188
	v_mul_f32_e32 v226, v16, v7
	v_mul_f32_e32 v227, v32, v7
	v_fmac_f32_e32 v226, v17, v8
	v_fmac_f32_e32 v227, v33, v8
	v_lshlrev_b32_e32 v5, 16, v196
	v_and_b32_e32 v6, 0xffff0000, v196
	v_mul_f32_e32 v228, v16, v5
	v_mul_f32_e32 v229, v32, v5
	v_fmac_f32_e32 v228, v17, v6
	v_fmac_f32_e32 v229, v33, v6
	v_lshlrev_b32_e32 v5, 16, v133
	v_and_b32_e32 v6, 0xffff0000, v133
	v_fmac_f32_e32 v212, v18, v5
	v_fmac_f32_e32 v213, v34, v5
	v_fmac_f32_e32 v212, v19, v6
	v_fmac_f32_e32 v213, v35, v6
	v_lshlrev_b32_e32 v7, 16, v141
	v_and_b32_e32 v8, 0xffff0000, v141
	v_fmac_f32_e32 v214, v18, v7
	v_fmac_f32_e32 v215, v34, v7
	v_fmac_f32_e32 v214, v19, v8
	v_fmac_f32_e32 v215, v35, v8
	v_lshlrev_b32_e32 v5, 16, v149
	v_and_b32_e32 v6, 0xffff0000, v149
	v_fmac_f32_e32 v216, v18, v5
	v_fmac_f32_e32 v217, v34, v5
	v_fmac_f32_e32 v216, v19, v6
	v_fmac_f32_e32 v217, v35, v6
	v_lshlrev_b32_e32 v7, 16, v157
	v_and_b32_e32 v8, 0xffff0000, v157
	v_fmac_f32_e32 v218, v18, v7
	v_fmac_f32_e32 v219, v34, v7
	v_fmac_f32_e32 v218, v19, v8
	v_fmac_f32_e32 v219, v35, v8
	v_lshlrev_b32_e32 v5, 16, v165
	v_and_b32_e32 v6, 0xffff0000, v165
	v_fmac_f32_e32 v220, v18, v5
	v_fmac_f32_e32 v221, v34, v5
	v_fmac_f32_e32 v220, v19, v6
	v_fmac_f32_e32 v221, v35, v6
	v_lshlrev_b32_e32 v7, 16, v173
	v_and_b32_e32 v8, 0xffff0000, v173
	v_fmac_f32_e32 v222, v18, v7
	v_fmac_f32_e32 v223, v34, v7
	v_fmac_f32_e32 v222, v19, v8
	v_fmac_f32_e32 v223, v35, v8
	v_lshlrev_b32_e32 v5, 16, v181
	v_and_b32_e32 v6, 0xffff0000, v181
	v_fmac_f32_e32 v224, v18, v5
	v_fmac_f32_e32 v225, v34, v5
	v_fmac_f32_e32 v224, v19, v6
	v_fmac_f32_e32 v225, v35, v6
	v_lshlrev_b32_e32 v7, 16, v189
	v_and_b32_e32 v8, 0xffff0000, v189
	v_fmac_f32_e32 v226, v18, v7
	v_fmac_f32_e32 v227, v34, v7
	v_fmac_f32_e32 v226, v19, v8
	v_fmac_f32_e32 v227, v35, v8
	v_lshlrev_b32_e32 v5, 16, v197
	v_and_b32_e32 v6, 0xffff0000, v197
	v_fmac_f32_e32 v228, v18, v5
	v_fmac_f32_e32 v229, v34, v5
	v_fmac_f32_e32 v228, v19, v6
	v_fmac_f32_e32 v229, v35, v6
	v_lshlrev_b32_e32 v5, 16, v134
	v_and_b32_e32 v6, 0xffff0000, v134
	v_fmac_f32_e32 v212, v20, v5
	v_fmac_f32_e32 v213, v36, v5
	v_fmac_f32_e32 v212, v21, v6
	v_fmac_f32_e32 v213, v37, v6
	v_lshlrev_b32_e32 v7, 16, v142
	v_and_b32_e32 v8, 0xffff0000, v142
	v_fmac_f32_e32 v214, v20, v7
	v_fmac_f32_e32 v215, v36, v7
	v_fmac_f32_e32 v214, v21, v8
	v_fmac_f32_e32 v215, v37, v8
	v_lshlrev_b32_e32 v5, 16, v150
	v_and_b32_e32 v6, 0xffff0000, v150
	v_fmac_f32_e32 v216, v20, v5
	v_fmac_f32_e32 v217, v36, v5
	v_fmac_f32_e32 v216, v21, v6
	v_fmac_f32_e32 v217, v37, v6
	v_lshlrev_b32_e32 v7, 16, v158
	v_and_b32_e32 v8, 0xffff0000, v158
	v_fmac_f32_e32 v218, v20, v7
	v_fmac_f32_e32 v219, v36, v7
	v_fmac_f32_e32 v218, v21, v8
	v_fmac_f32_e32 v219, v37, v8
	v_lshlrev_b32_e32 v5, 16, v166
	v_and_b32_e32 v6, 0xffff0000, v166
	v_fmac_f32_e32 v220, v20, v5
	v_fmac_f32_e32 v221, v36, v5
	v_fmac_f32_e32 v220, v21, v6
	v_fmac_f32_e32 v221, v37, v6
	v_lshlrev_b32_e32 v7, 16, v174
	v_and_b32_e32 v8, 0xffff0000, v174
	v_fmac_f32_e32 v222, v20, v7
	v_fmac_f32_e32 v223, v36, v7
	v_fmac_f32_e32 v222, v21, v8
	v_fmac_f32_e32 v223, v37, v8
	v_lshlrev_b32_e32 v5, 16, v182
	v_and_b32_e32 v6, 0xffff0000, v182
	v_fmac_f32_e32 v224, v20, v5
	v_fmac_f32_e32 v225, v36, v5
	v_fmac_f32_e32 v224, v21, v6
	v_fmac_f32_e32 v225, v37, v6
	v_lshlrev_b32_e32 v7, 16, v190
	v_and_b32_e32 v8, 0xffff0000, v190
	v_fmac_f32_e32 v226, v20, v7
	v_fmac_f32_e32 v227, v36, v7
	v_fmac_f32_e32 v226, v21, v8
	v_fmac_f32_e32 v227, v37, v8
	v_lshlrev_b32_e32 v5, 16, v198
	v_and_b32_e32 v6, 0xffff0000, v198
	v_fmac_f32_e32 v228, v20, v5
	v_fmac_f32_e32 v229, v36, v5
	v_fmac_f32_e32 v228, v21, v6
	v_fmac_f32_e32 v229, v37, v6
	v_lshlrev_b32_e32 v5, 16, v135
	v_and_b32_e32 v6, 0xffff0000, v135
	v_fmac_f32_e32 v212, v22, v5
	v_fmac_f32_e32 v213, v38, v5
	v_fmac_f32_e32 v212, v23, v6
	v_fmac_f32_e32 v213, v39, v6
	v_lshlrev_b32_e32 v7, 16, v143
	v_and_b32_e32 v8, 0xffff0000, v143
	v_fmac_f32_e32 v214, v22, v7
	v_fmac_f32_e32 v215, v38, v7
	v_fmac_f32_e32 v214, v23, v8
	v_fmac_f32_e32 v215, v39, v8
	v_lshlrev_b32_e32 v5, 16, v151
	v_and_b32_e32 v6, 0xffff0000, v151
	v_fmac_f32_e32 v216, v22, v5
	v_fmac_f32_e32 v217, v38, v5
	v_fmac_f32_e32 v216, v23, v6
	v_fmac_f32_e32 v217, v39, v6
	v_lshlrev_b32_e32 v7, 16, v159
	v_and_b32_e32 v8, 0xffff0000, v159
	v_fmac_f32_e32 v218, v22, v7
	v_fmac_f32_e32 v219, v38, v7
	v_fmac_f32_e32 v218, v23, v8
	v_fmac_f32_e32 v219, v39, v8
	v_lshlrev_b32_e32 v5, 16, v167
	v_and_b32_e32 v6, 0xffff0000, v167
	v_fmac_f32_e32 v220, v22, v5
	v_fmac_f32_e32 v221, v38, v5
	v_fmac_f32_e32 v220, v23, v6
	v_fmac_f32_e32 v221, v39, v6
	v_lshlrev_b32_e32 v7, 16, v175
	v_and_b32_e32 v8, 0xffff0000, v175
	v_fmac_f32_e32 v222, v22, v7
	v_fmac_f32_e32 v223, v38, v7
	v_fmac_f32_e32 v222, v23, v8
	v_fmac_f32_e32 v223, v39, v8
	v_lshlrev_b32_e32 v5, 16, v183
	v_and_b32_e32 v6, 0xffff0000, v183
	v_fmac_f32_e32 v224, v22, v5
	v_fmac_f32_e32 v225, v38, v5
	v_fmac_f32_e32 v224, v23, v6
	v_fmac_f32_e32 v225, v39, v6
	v_lshlrev_b32_e32 v7, 16, v191
	v_and_b32_e32 v8, 0xffff0000, v191
	v_fmac_f32_e32 v226, v22, v7
	v_fmac_f32_e32 v227, v38, v7
	v_fmac_f32_e32 v226, v23, v8
	v_fmac_f32_e32 v227, v39, v8
	v_lshlrev_b32_e32 v5, 16, v199
	v_and_b32_e32 v6, 0xffff0000, v199
	v_fmac_f32_e32 v228, v22, v5
	v_fmac_f32_e32 v229, v38, v5
	v_fmac_f32_e32 v228, v23, v6
	v_fmac_f32_e32 v229, v39, v6
	v_lshlrev_b32_e32 v5, 16, v136
	v_and_b32_e32 v6, 0xffff0000, v136
	v_fmac_f32_e32 v212, v24, v5
	v_fmac_f32_e32 v213, v40, v5
	v_fmac_f32_e32 v212, v25, v6
	v_fmac_f32_e32 v213, v41, v6
	v_lshlrev_b32_e32 v7, 16, v144
	v_and_b32_e32 v8, 0xffff0000, v144
	v_fmac_f32_e32 v214, v24, v7
	v_fmac_f32_e32 v215, v40, v7
	v_fmac_f32_e32 v214, v25, v8
	v_fmac_f32_e32 v215, v41, v8
	v_lshlrev_b32_e32 v5, 16, v152
	v_and_b32_e32 v6, 0xffff0000, v152
	v_fmac_f32_e32 v216, v24, v5
	v_fmac_f32_e32 v217, v40, v5
	v_fmac_f32_e32 v216, v25, v6
	v_fmac_f32_e32 v217, v41, v6
	v_lshlrev_b32_e32 v7, 16, v160
	v_and_b32_e32 v8, 0xffff0000, v160
	v_fmac_f32_e32 v218, v24, v7
	v_fmac_f32_e32 v219, v40, v7
	v_fmac_f32_e32 v218, v25, v8
	v_fmac_f32_e32 v219, v41, v8
	v_lshlrev_b32_e32 v5, 16, v168
	v_and_b32_e32 v6, 0xffff0000, v168
	v_fmac_f32_e32 v220, v24, v5
	v_fmac_f32_e32 v221, v40, v5
	v_fmac_f32_e32 v220, v25, v6
	v_fmac_f32_e32 v221, v41, v6
	v_lshlrev_b32_e32 v7, 16, v176
	v_and_b32_e32 v8, 0xffff0000, v176
	v_fmac_f32_e32 v222, v24, v7
	v_fmac_f32_e32 v223, v40, v7
	v_fmac_f32_e32 v222, v25, v8
	v_fmac_f32_e32 v223, v41, v8
	v_lshlrev_b32_e32 v5, 16, v184
	v_and_b32_e32 v6, 0xffff0000, v184
	v_fmac_f32_e32 v224, v24, v5
	v_fmac_f32_e32 v225, v40, v5
	v_fmac_f32_e32 v224, v25, v6
	v_fmac_f32_e32 v225, v41, v6
	v_lshlrev_b32_e32 v7, 16, v192
	v_and_b32_e32 v8, 0xffff0000, v192
	v_fmac_f32_e32 v226, v24, v7
	v_fmac_f32_e32 v227, v40, v7
	v_fmac_f32_e32 v226, v25, v8
	v_fmac_f32_e32 v227, v41, v8
	v_lshlrev_b32_e32 v5, 16, v200
	v_and_b32_e32 v6, 0xffff0000, v200
	v_fmac_f32_e32 v228, v24, v5
	v_fmac_f32_e32 v229, v40, v5
	v_fmac_f32_e32 v228, v25, v6
	v_fmac_f32_e32 v229, v41, v6
	v_lshlrev_b32_e32 v5, 16, v137
	v_and_b32_e32 v6, 0xffff0000, v137
	v_fmac_f32_e32 v212, v26, v5
	v_fmac_f32_e32 v213, v42, v5
	v_fmac_f32_e32 v212, v27, v6
	v_fmac_f32_e32 v213, v43, v6
	v_lshlrev_b32_e32 v7, 16, v145
	v_and_b32_e32 v8, 0xffff0000, v145
	v_fmac_f32_e32 v214, v26, v7
	v_fmac_f32_e32 v215, v42, v7
	v_fmac_f32_e32 v214, v27, v8
	v_fmac_f32_e32 v215, v43, v8
	v_lshlrev_b32_e32 v5, 16, v153
	v_and_b32_e32 v6, 0xffff0000, v153
	v_fmac_f32_e32 v216, v26, v5
	v_fmac_f32_e32 v217, v42, v5
	v_fmac_f32_e32 v216, v27, v6
	v_fmac_f32_e32 v217, v43, v6
	v_lshlrev_b32_e32 v7, 16, v161
	v_and_b32_e32 v8, 0xffff0000, v161
	v_fmac_f32_e32 v218, v26, v7
	v_fmac_f32_e32 v219, v42, v7
	v_fmac_f32_e32 v218, v27, v8
	v_fmac_f32_e32 v219, v43, v8
	v_lshlrev_b32_e32 v5, 16, v169
	v_and_b32_e32 v6, 0xffff0000, v169
	v_fmac_f32_e32 v220, v26, v5
	v_fmac_f32_e32 v221, v42, v5
	v_fmac_f32_e32 v220, v27, v6
	v_fmac_f32_e32 v221, v43, v6
	v_lshlrev_b32_e32 v7, 16, v177
	v_and_b32_e32 v8, 0xffff0000, v177
	v_fmac_f32_e32 v222, v26, v7
	v_fmac_f32_e32 v223, v42, v7
	v_fmac_f32_e32 v222, v27, v8
	v_fmac_f32_e32 v223, v43, v8
	v_lshlrev_b32_e32 v5, 16, v185
	v_and_b32_e32 v6, 0xffff0000, v185
	v_fmac_f32_e32 v224, v26, v5
	v_fmac_f32_e32 v225, v42, v5
	v_fmac_f32_e32 v224, v27, v6
	v_fmac_f32_e32 v225, v43, v6
	v_lshlrev_b32_e32 v7, 16, v193
	v_and_b32_e32 v8, 0xffff0000, v193
	v_fmac_f32_e32 v226, v26, v7
	v_fmac_f32_e32 v227, v42, v7
	v_fmac_f32_e32 v226, v27, v8
	v_fmac_f32_e32 v227, v43, v8
	v_lshlrev_b32_e32 v5, 16, v201
	v_and_b32_e32 v6, 0xffff0000, v201
	v_fmac_f32_e32 v228, v26, v5
	v_fmac_f32_e32 v229, v42, v5
	v_fmac_f32_e32 v228, v27, v6
	v_fmac_f32_e32 v229, v43, v6
	v_lshlrev_b32_e32 v5, 16, v138
	v_and_b32_e32 v6, 0xffff0000, v138
	v_fmac_f32_e32 v212, v28, v5
	v_fmac_f32_e32 v213, v44, v5
	v_fmac_f32_e32 v212, v29, v6
	v_fmac_f32_e32 v213, v45, v6
	v_lshlrev_b32_e32 v7, 16, v146
	v_and_b32_e32 v8, 0xffff0000, v146
	v_fmac_f32_e32 v214, v28, v7
	v_fmac_f32_e32 v215, v44, v7
	v_fmac_f32_e32 v214, v29, v8
	v_fmac_f32_e32 v215, v45, v8
	v_lshlrev_b32_e32 v5, 16, v154
	v_and_b32_e32 v6, 0xffff0000, v154
	v_fmac_f32_e32 v216, v28, v5
	v_fmac_f32_e32 v217, v44, v5
	v_fmac_f32_e32 v216, v29, v6
	v_fmac_f32_e32 v217, v45, v6
	v_lshlrev_b32_e32 v7, 16, v162
	v_and_b32_e32 v8, 0xffff0000, v162
	v_fmac_f32_e32 v218, v28, v7
	v_fmac_f32_e32 v219, v44, v7
	v_fmac_f32_e32 v218, v29, v8
	v_fmac_f32_e32 v219, v45, v8
	v_lshlrev_b32_e32 v5, 16, v170
	v_and_b32_e32 v6, 0xffff0000, v170
	v_fmac_f32_e32 v220, v28, v5
	v_fmac_f32_e32 v221, v44, v5
	v_fmac_f32_e32 v220, v29, v6
	v_fmac_f32_e32 v221, v45, v6
	v_lshlrev_b32_e32 v7, 16, v178
	v_and_b32_e32 v8, 0xffff0000, v178
	v_fmac_f32_e32 v222, v28, v7
	v_fmac_f32_e32 v223, v44, v7
	v_fmac_f32_e32 v222, v29, v8
	v_fmac_f32_e32 v223, v45, v8
	v_lshlrev_b32_e32 v5, 16, v186
	v_and_b32_e32 v6, 0xffff0000, v186
	v_fmac_f32_e32 v224, v28, v5
	v_fmac_f32_e32 v225, v44, v5
	v_fmac_f32_e32 v224, v29, v6
	v_fmac_f32_e32 v225, v45, v6
	v_lshlrev_b32_e32 v7, 16, v194
	v_and_b32_e32 v8, 0xffff0000, v194
	v_fmac_f32_e32 v226, v28, v7
	v_fmac_f32_e32 v227, v44, v7
	v_fmac_f32_e32 v226, v29, v8
	v_fmac_f32_e32 v227, v45, v8
	v_lshlrev_b32_e32 v5, 16, v202
	v_and_b32_e32 v6, 0xffff0000, v202
	v_fmac_f32_e32 v228, v28, v5
	v_fmac_f32_e32 v229, v44, v5
	v_fmac_f32_e32 v228, v29, v6
	v_fmac_f32_e32 v229, v45, v6
	v_lshlrev_b32_e32 v5, 16, v139
	v_and_b32_e32 v6, 0xffff0000, v139
	v_fmac_f32_e32 v212, v30, v5
	v_fmac_f32_e32 v213, v46, v5
	v_fmac_f32_e32 v212, v31, v6
	v_fmac_f32_e32 v213, v47, v6
	v_lshlrev_b32_e32 v7, 16, v147
	v_and_b32_e32 v8, 0xffff0000, v147
	v_fmac_f32_e32 v214, v30, v7
	v_fmac_f32_e32 v215, v46, v7
	v_fmac_f32_e32 v214, v31, v8
	v_fmac_f32_e32 v215, v47, v8
	v_lshlrev_b32_e32 v5, 16, v155
	v_and_b32_e32 v6, 0xffff0000, v155
	v_fmac_f32_e32 v216, v30, v5
	v_fmac_f32_e32 v217, v46, v5
	v_fmac_f32_e32 v216, v31, v6
	v_fmac_f32_e32 v217, v47, v6
	v_lshlrev_b32_e32 v7, 16, v163
	v_and_b32_e32 v8, 0xffff0000, v163
	v_fmac_f32_e32 v218, v30, v7
	v_fmac_f32_e32 v219, v46, v7
	v_fmac_f32_e32 v218, v31, v8
	v_fmac_f32_e32 v219, v47, v8
	v_lshlrev_b32_e32 v5, 16, v171
	v_and_b32_e32 v6, 0xffff0000, v171
	v_fmac_f32_e32 v220, v30, v5
	v_fmac_f32_e32 v221, v46, v5
	v_fmac_f32_e32 v220, v31, v6
	v_fmac_f32_e32 v221, v47, v6
	v_lshlrev_b32_e32 v7, 16, v179
	v_and_b32_e32 v8, 0xffff0000, v179
	v_fmac_f32_e32 v222, v30, v7
	v_fmac_f32_e32 v223, v46, v7
	v_fmac_f32_e32 v222, v31, v8
	v_fmac_f32_e32 v223, v47, v8
	v_lshlrev_b32_e32 v5, 16, v187
	v_and_b32_e32 v6, 0xffff0000, v187
	v_fmac_f32_e32 v224, v30, v5
	v_fmac_f32_e32 v225, v46, v5
	v_fmac_f32_e32 v224, v31, v6
	v_fmac_f32_e32 v225, v47, v6
	v_lshlrev_b32_e32 v7, 16, v195
	v_and_b32_e32 v8, 0xffff0000, v195
	v_fmac_f32_e32 v226, v30, v7
	v_fmac_f32_e32 v227, v46, v7
	v_fmac_f32_e32 v226, v31, v8
	v_fmac_f32_e32 v227, v47, v8
	v_lshlrev_b32_e32 v5, 16, v203
	v_and_b32_e32 v6, 0xffff0000, v203
	v_fmac_f32_e32 v228, v30, v5
	v_fmac_f32_e32 v229, v46, v5
	v_fmac_f32_e32 v228, v31, v6
	v_fmac_f32_e32 v229, v47, v6
	global_load_dwordx4 v[132:135], v1, s[28:29]
	global_load_dwordx4 v[136:139], v1, s[28:29] offset:16
	s_add_u32 s28, s28, 0x80000
	s_addc_u32 s29, s29, 0
	global_load_dwordx4 v[140:143], v1, s[28:29]
	global_load_dwordx4 v[144:147], v1, s[28:29] offset:16
	s_add_u32 s28, s28, 0x80000
	s_addc_u32 s29, s29, 0
	global_load_dwordx4 v[148:151], v1, s[28:29]
	global_load_dwordx4 v[152:155], v1, s[28:29] offset:16
	s_add_u32 s28, s28, 0x80000
	s_addc_u32 s29, s29, 0
	global_load_dwordx4 v[156:159], v1, s[28:29]
	global_load_dwordx4 v[160:163], v1, s[28:29] offset:16
	s_add_u32 s28, s28, 0x80000
	s_addc_u32 s29, s29, 0
	v_add_f32_dpp v212, v212, v212 quad_perm:[1,0,3,2] row_mask:0xf bank_mask:0xf
	v_add_f32_dpp v213, v213, v213 quad_perm:[1,0,3,2] row_mask:0xf bank_mask:0xf
	v_add_f32_dpp v214, v214, v214 quad_perm:[1,0,3,2] row_mask:0xf bank_mask:0xf
	v_add_f32_dpp v215, v215, v215 quad_perm:[1,0,3,2] row_mask:0xf bank_mask:0xf
	v_add_f32_dpp v216, v216, v216 quad_perm:[1,0,3,2] row_mask:0xf bank_mask:0xf
	v_add_f32_dpp v217, v217, v217 quad_perm:[1,0,3,2] row_mask:0xf bank_mask:0xf
	v_add_f32_dpp v218, v218, v218 quad_perm:[1,0,3,2] row_mask:0xf bank_mask:0xf
	v_add_f32_dpp v219, v219, v219 quad_perm:[1,0,3,2] row_mask:0xf bank_mask:0xf
	v_add_f32_dpp v220, v220, v220 quad_perm:[1,0,3,2] row_mask:0xf bank_mask:0xf
	v_add_f32_dpp v221, v221, v221 quad_perm:[1,0,3,2] row_mask:0xf bank_mask:0xf
	v_add_f32_dpp v222, v222, v222 quad_perm:[1,0,3,2] row_mask:0xf bank_mask:0xf
	v_add_f32_dpp v223, v223, v223 quad_perm:[1,0,3,2] row_mask:0xf bank_mask:0xf
	v_add_f32_dpp v224, v224, v224 quad_perm:[1,0,3,2] row_mask:0xf bank_mask:0xf
	v_add_f32_dpp v225, v225, v225 quad_perm:[1,0,3,2] row_mask:0xf bank_mask:0xf
	v_add_f32_dpp v226, v226, v226 quad_perm:[1,0,3,2] row_mask:0xf bank_mask:0xf
	v_add_f32_dpp v227, v227, v227 quad_perm:[1,0,3,2] row_mask:0xf bank_mask:0xf
	v_add_f32_dpp v228, v228, v228 quad_perm:[1,0,3,2] row_mask:0xf bank_mask:0xf
	v_add_f32_dpp v229, v229, v229 quad_perm:[1,0,3,2] row_mask:0xf bank_mask:0xf
	v_add_f32_dpp v212, v212, v212 quad_perm:[2,3,0,1] row_mask:0xf bank_mask:0xf
	v_add_f32_dpp v213, v213, v213 quad_perm:[2,3,0,1] row_mask:0xf bank_mask:0xf
	v_add_f32_dpp v214, v214, v214 quad_perm:[2,3,0,1] row_mask:0xf bank_mask:0xf
	v_add_f32_dpp v215, v215, v215 quad_perm:[2,3,0,1] row_mask:0xf bank_mask:0xf
	v_add_f32_dpp v216, v216, v216 quad_perm:[2,3,0,1] row_mask:0xf bank_mask:0xf
	v_add_f32_dpp v217, v217, v217 quad_perm:[2,3,0,1] row_mask:0xf bank_mask:0xf
	v_add_f32_dpp v218, v218, v218 quad_perm:[2,3,0,1] row_mask:0xf bank_mask:0xf
	v_add_f32_dpp v219, v219, v219 quad_perm:[2,3,0,1] row_mask:0xf bank_mask:0xf
	v_add_f32_dpp v220, v220, v220 quad_perm:[2,3,0,1] row_mask:0xf bank_mask:0xf
	v_add_f32_dpp v221, v221, v221 quad_perm:[2,3,0,1] row_mask:0xf bank_mask:0xf
	v_add_f32_dpp v222, v222, v222 quad_perm:[2,3,0,1] row_mask:0xf bank_mask:0xf
	v_add_f32_dpp v223, v223, v223 quad_perm:[2,3,0,1] row_mask:0xf bank_mask:0xf
	v_add_f32_dpp v224, v224, v224 quad_perm:[2,3,0,1] row_mask:0xf bank_mask:0xf
	v_add_f32_dpp v225, v225, v225 quad_perm:[2,3,0,1] row_mask:0xf bank_mask:0xf
	v_add_f32_dpp v226, v226, v226 quad_perm:[2,3,0,1] row_mask:0xf bank_mask:0xf
	v_add_f32_dpp v227, v227, v227 quad_perm:[2,3,0,1] row_mask:0xf bank_mask:0xf
	v_add_f32_dpp v228, v228, v228 quad_perm:[2,3,0,1] row_mask:0xf bank_mask:0xf
	v_add_f32_dpp v229, v229, v229 quad_perm:[2,3,0,1] row_mask:0xf bank_mask:0xf
	v_add_f32_dpp v212, v212, v212 row_half_mirror row_mask:0xf bank_mask:0xf
	v_add_f32_dpp v213, v213, v213 row_half_mirror row_mask:0xf bank_mask:0xf
	v_add_f32_dpp v214, v214, v214 row_half_mirror row_mask:0xf bank_mask:0xf
	v_add_f32_dpp v215, v215, v215 row_half_mirror row_mask:0xf bank_mask:0xf
	v_add_f32_dpp v216, v216, v216 row_half_mirror row_mask:0xf bank_mask:0xf
	v_add_f32_dpp v217, v217, v217 row_half_mirror row_mask:0xf bank_mask:0xf
	v_add_f32_dpp v218, v218, v218 row_half_mirror row_mask:0xf bank_mask:0xf
	v_add_f32_dpp v219, v219, v219 row_half_mirror row_mask:0xf bank_mask:0xf
	v_add_f32_dpp v220, v220, v220 row_half_mirror row_mask:0xf bank_mask:0xf
	v_add_f32_dpp v221, v221, v221 row_half_mirror row_mask:0xf bank_mask:0xf
	v_add_f32_dpp v222, v222, v222 row_half_mirror row_mask:0xf bank_mask:0xf
	v_add_f32_dpp v223, v223, v223 row_half_mirror row_mask:0xf bank_mask:0xf
	v_add_f32_dpp v224, v224, v224 row_half_mirror row_mask:0xf bank_mask:0xf
	v_add_f32_dpp v225, v225, v225 row_half_mirror row_mask:0xf bank_mask:0xf
	v_add_f32_dpp v226, v226, v226 row_half_mirror row_mask:0xf bank_mask:0xf
	v_add_f32_dpp v227, v227, v227 row_half_mirror row_mask:0xf bank_mask:0xf
	v_add_f32_dpp v228, v228, v228 row_half_mirror row_mask:0xf bank_mask:0xf
	v_add_f32_dpp v229, v229, v229 row_half_mirror row_mask:0xf bank_mask:0xf
	v_add_f32_dpp v212, v212, v212 row_mirror row_mask:0xf bank_mask:0xf
	v_add_f32_dpp v213, v213, v213 row_mirror row_mask:0xf bank_mask:0xf
	v_add_f32_dpp v214, v214, v214 row_mirror row_mask:0xf bank_mask:0xf
	v_add_f32_dpp v215, v215, v215 row_mirror row_mask:0xf bank_mask:0xf
	v_add_f32_dpp v216, v216, v216 row_mirror row_mask:0xf bank_mask:0xf
	v_add_f32_dpp v217, v217, v217 row_mirror row_mask:0xf bank_mask:0xf
	v_add_f32_dpp v218, v218, v218 row_mirror row_mask:0xf bank_mask:0xf
	v_add_f32_dpp v219, v219, v219 row_mirror row_mask:0xf bank_mask:0xf
	v_add_f32_dpp v220, v220, v220 row_mirror row_mask:0xf bank_mask:0xf
	v_add_f32_dpp v221, v221, v221 row_mirror row_mask:0xf bank_mask:0xf
	v_add_f32_dpp v222, v222, v222 row_mirror row_mask:0xf bank_mask:0xf
	v_add_f32_dpp v223, v223, v223 row_mirror row_mask:0xf bank_mask:0xf
	v_add_f32_dpp v224, v224, v224 row_mirror row_mask:0xf bank_mask:0xf
	v_add_f32_dpp v225, v225, v225 row_mirror row_mask:0xf bank_mask:0xf
	v_add_f32_dpp v226, v226, v226 row_mirror row_mask:0xf bank_mask:0xf
	v_add_f32_dpp v227, v227, v227 row_mirror row_mask:0xf bank_mask:0xf
	v_add_f32_dpp v228, v228, v228 row_mirror row_mask:0xf bank_mask:0xf
	v_add_f32_dpp v229, v229, v229 row_mirror row_mask:0xf bank_mask:0xf
	v_add_f32_dpp v212, v212, v212 row_bcast:15 row_mask:0xa bank_mask:0xf
	v_add_f32_dpp v213, v213, v213 row_bcast:15 row_mask:0xa bank_mask:0xf
	v_add_f32_dpp v214, v214, v214 row_bcast:15 row_mask:0xa bank_mask:0xf
	v_add_f32_dpp v215, v215, v215 row_bcast:15 row_mask:0xa bank_mask:0xf
	v_add_f32_dpp v216, v216, v216 row_bcast:15 row_mask:0xa bank_mask:0xf
	v_add_f32_dpp v217, v217, v217 row_bcast:15 row_mask:0xa bank_mask:0xf
	v_add_f32_dpp v218, v218, v218 row_bcast:15 row_mask:0xa bank_mask:0xf
	v_add_f32_dpp v219, v219, v219 row_bcast:15 row_mask:0xa bank_mask:0xf
	v_add_f32_dpp v220, v220, v220 row_bcast:15 row_mask:0xa bank_mask:0xf
	v_add_f32_dpp v221, v221, v221 row_bcast:15 row_mask:0xa bank_mask:0xf
	v_add_f32_dpp v222, v222, v222 row_bcast:15 row_mask:0xa bank_mask:0xf
	v_add_f32_dpp v223, v223, v223 row_bcast:15 row_mask:0xa bank_mask:0xf
	v_add_f32_dpp v224, v224, v224 row_bcast:15 row_mask:0xa bank_mask:0xf
	v_add_f32_dpp v225, v225, v225 row_bcast:15 row_mask:0xa bank_mask:0xf
	v_add_f32_dpp v226, v226, v226 row_bcast:15 row_mask:0xa bank_mask:0xf
	v_add_f32_dpp v227, v227, v227 row_bcast:15 row_mask:0xa bank_mask:0xf
	v_add_f32_dpp v228, v228, v228 row_bcast:15 row_mask:0xa bank_mask:0xf
	v_add_f32_dpp v229, v229, v229 row_bcast:15 row_mask:0xa bank_mask:0xf
	v_add_f32_dpp v212, v212, v212 row_bcast:31 row_mask:0xc bank_mask:0xf
	v_add_f32_dpp v213, v213, v213 row_bcast:31 row_mask:0xc bank_mask:0xf
	v_add_f32_dpp v214, v214, v214 row_bcast:31 row_mask:0xc bank_mask:0xf
	v_add_f32_dpp v215, v215, v215 row_bcast:31 row_mask:0xc bank_mask:0xf
	v_add_f32_dpp v216, v216, v216 row_bcast:31 row_mask:0xc bank_mask:0xf
	v_add_f32_dpp v217, v217, v217 row_bcast:31 row_mask:0xc bank_mask:0xf
	v_add_f32_dpp v218, v218, v218 row_bcast:31 row_mask:0xc bank_mask:0xf
	v_add_f32_dpp v219, v219, v219 row_bcast:31 row_mask:0xc bank_mask:0xf
	v_add_f32_dpp v220, v220, v220 row_bcast:31 row_mask:0xc bank_mask:0xf
	v_add_f32_dpp v221, v221, v221 row_bcast:31 row_mask:0xc bank_mask:0xf
	v_add_f32_dpp v222, v222, v222 row_bcast:31 row_mask:0xc bank_mask:0xf
	v_add_f32_dpp v223, v223, v223 row_bcast:31 row_mask:0xc bank_mask:0xf
	v_add_f32_dpp v224, v224, v224 row_bcast:31 row_mask:0xc bank_mask:0xf
	v_add_f32_dpp v225, v225, v225 row_bcast:31 row_mask:0xc bank_mask:0xf
	v_add_f32_dpp v226, v226, v226 row_bcast:31 row_mask:0xc bank_mask:0xf
	v_add_f32_dpp v227, v227, v227 row_bcast:31 row_mask:0xc bank_mask:0xf
	v_add_f32_dpp v228, v228, v228 row_bcast:31 row_mask:0xc bank_mask:0xf
	v_add_f32_dpp v229, v229, v229 row_bcast:31 row_mask:0xc bank_mask:0xf
	s_nop 0
	v_readlane_b32 s32, v212, 63
	v_readlane_b32 s33, v213, 63
	v_readlane_b32 s40, v214, 63
	v_readlane_b32 s41, v215, 63
	v_readlane_b32 s46, v216, 63
	v_readlane_b32 s47, v217, 63
	v_readlane_b32 s51, v218, 63
	v_readlane_b32 s57, v219, 63
	v_readlane_b32 s58, v220, 63
	v_readlane_b32 s59, v221, 63
	v_readlane_b32 s60, v222, 63
	v_readlane_b32 s61, v223, 63
	v_readlane_b32 s62, v224, 63
	v_readlane_b32 s63, v225, 63
	v_readlane_b32 s70, v226, 63
	v_readlane_b32 s71, v227, 63
	v_readlane_b32 s74, v228, 63
	v_readlane_b32 s75, v229, 63
	s_nop 1
	v_writelane_b32 v9, s32, 0
	v_writelane_b32 v9, s33, 1
	v_writelane_b32 v9, s40, 2
	v_writelane_b32 v9, s41, 3
	v_writelane_b32 v9, s46, 4
	v_writelane_b32 v9, s47, 5
	v_writelane_b32 v9, s51, 6
	v_writelane_b32 v9, s57, 7
	v_writelane_b32 v9, s58, 8
	v_writelane_b32 v9, s59, 9
	v_writelane_b32 v9, s60, 10
	v_writelane_b32 v9, s61, 11
	v_writelane_b32 v9, s62, 12
	v_writelane_b32 v9, s63, 13
	v_writelane_b32 v9, s70, 14
	v_writelane_b32 v9, s71, 15
	v_writelane_b32 v9, s74, 16
	v_writelane_b32 v9, s75, 17
	s_mul_i32 s91, s3, 11264
	s_add_i32 s91, s91, s5
	s_add_i32 s91, s91, 2304
	s_add_u32 s8, s0, 0x3e00000
	s_addc_u32 s9, s1, 0
	v_add_u32_e32 v15, s91, v14
	v_lshlrev_b32_e32 v15, 2, v15
	s_mov_b64 exec, 0x3ffff
	global_store_dword v15, v9, s[8:9]
	s_mov_b64 exec, -1
	s_waitcnt vmcnt(0)
	v_lshlrev_b32_e32 v5, 16, v132
	v_and_b32_e32 v6, 0xffff0000, v132
	v_mul_f32_e32 v212, v16, v5
	v_mul_f32_e32 v213, v32, v5
	v_fmac_f32_e32 v212, v17, v6
	v_fmac_f32_e32 v213, v33, v6
	v_lshlrev_b32_e32 v7, 16, v140
	v_and_b32_e32 v8, 0xffff0000, v140
	v_mul_f32_e32 v214, v16, v7
	v_mul_f32_e32 v215, v32, v7
	v_fmac_f32_e32 v214, v17, v8
	v_fmac_f32_e32 v215, v33, v8
	v_lshlrev_b32_e32 v5, 16, v148
	v_and_b32_e32 v6, 0xffff0000, v148
	v_mul_f32_e32 v216, v16, v5
	v_mul_f32_e32 v217, v32, v5
	v_fmac_f32_e32 v216, v17, v6
	v_fmac_f32_e32 v217, v33, v6
	v_lshlrev_b32_e32 v7, 16, v156
	v_and_b32_e32 v8, 0xffff0000, v156
	v_mul_f32_e32 v218, v16, v7
	v_mul_f32_e32 v219, v32, v7
	v_fmac_f32_e32 v218, v17, v8
	v_fmac_f32_e32 v219, v33, v8
	v_lshlrev_b32_e32 v5, 16, v133
	v_and_b32_e32 v6, 0xffff0000, v133
	v_fmac_f32_e32 v212, v18, v5
	v_fmac_f32_e32 v213, v34, v5
	v_fmac_f32_e32 v212, v19, v6
	v_fmac_f32_e32 v213, v35, v6
	v_lshlrev_b32_e32 v7, 16, v141
	v_and_b32_e32 v8, 0xffff0000, v141
	v_fmac_f32_e32 v214, v18, v7
	v_fmac_f32_e32 v215, v34, v7
	v_fmac_f32_e32 v214, v19, v8
	v_fmac_f32_e32 v215, v35, v8
	v_lshlrev_b32_e32 v5, 16, v149
	v_and_b32_e32 v6, 0xffff0000, v149
	v_fmac_f32_e32 v216, v18, v5
	v_fmac_f32_e32 v217, v34, v5
	v_fmac_f32_e32 v216, v19, v6
	v_fmac_f32_e32 v217, v35, v6
	v_lshlrev_b32_e32 v7, 16, v157
	v_and_b32_e32 v8, 0xffff0000, v157
	v_fmac_f32_e32 v218, v18, v7
	v_fmac_f32_e32 v219, v34, v7
	v_fmac_f32_e32 v218, v19, v8
	v_fmac_f32_e32 v219, v35, v8
	v_lshlrev_b32_e32 v5, 16, v134
	v_and_b32_e32 v6, 0xffff0000, v134
	v_fmac_f32_e32 v212, v20, v5
	v_fmac_f32_e32 v213, v36, v5
	v_fmac_f32_e32 v212, v21, v6
	v_fmac_f32_e32 v213, v37, v6
	v_lshlrev_b32_e32 v7, 16, v142
	v_and_b32_e32 v8, 0xffff0000, v142
	v_fmac_f32_e32 v214, v20, v7
	v_fmac_f32_e32 v215, v36, v7
	v_fmac_f32_e32 v214, v21, v8
	v_fmac_f32_e32 v215, v37, v8
	v_lshlrev_b32_e32 v5, 16, v150
	v_and_b32_e32 v6, 0xffff0000, v150
	v_fmac_f32_e32 v216, v20, v5
	v_fmac_f32_e32 v217, v36, v5
	v_fmac_f32_e32 v216, v21, v6
	v_fmac_f32_e32 v217, v37, v6
	v_lshlrev_b32_e32 v7, 16, v158
	v_and_b32_e32 v8, 0xffff0000, v158
	v_fmac_f32_e32 v218, v20, v7
	v_fmac_f32_e32 v219, v36, v7
	v_fmac_f32_e32 v218, v21, v8
	v_fmac_f32_e32 v219, v37, v8
	v_lshlrev_b32_e32 v5, 16, v135
	v_and_b32_e32 v6, 0xffff0000, v135
	v_fmac_f32_e32 v212, v22, v5
	v_fmac_f32_e32 v213, v38, v5
	v_fmac_f32_e32 v212, v23, v6
	v_fmac_f32_e32 v213, v39, v6
	v_lshlrev_b32_e32 v7, 16, v143
	v_and_b32_e32 v8, 0xffff0000, v143
	v_fmac_f32_e32 v214, v22, v7
	v_fmac_f32_e32 v215, v38, v7
	v_fmac_f32_e32 v214, v23, v8
	v_fmac_f32_e32 v215, v39, v8
	v_lshlrev_b32_e32 v5, 16, v151
	v_and_b32_e32 v6, 0xffff0000, v151
	v_fmac_f32_e32 v216, v22, v5
	v_fmac_f32_e32 v217, v38, v5
	v_fmac_f32_e32 v216, v23, v6
	v_fmac_f32_e32 v217, v39, v6
	v_lshlrev_b32_e32 v7, 16, v159
	v_and_b32_e32 v8, 0xffff0000, v159
	v_fmac_f32_e32 v218, v22, v7
	v_fmac_f32_e32 v219, v38, v7
	v_fmac_f32_e32 v218, v23, v8
	v_fmac_f32_e32 v219, v39, v8
	v_lshlrev_b32_e32 v5, 16, v136
	v_and_b32_e32 v6, 0xffff0000, v136
	v_fmac_f32_e32 v212, v24, v5
	v_fmac_f32_e32 v213, v40, v5
	v_fmac_f32_e32 v212, v25, v6
	v_fmac_f32_e32 v213, v41, v6
	v_lshlrev_b32_e32 v7, 16, v144
	v_and_b32_e32 v8, 0xffff0000, v144
	v_fmac_f32_e32 v214, v24, v7
	v_fmac_f32_e32 v215, v40, v7
	v_fmac_f32_e32 v214, v25, v8
	v_fmac_f32_e32 v215, v41, v8
	v_lshlrev_b32_e32 v5, 16, v152
	v_and_b32_e32 v6, 0xffff0000, v152
	v_fmac_f32_e32 v216, v24, v5
	v_fmac_f32_e32 v217, v40, v5
	v_fmac_f32_e32 v216, v25, v6
	v_fmac_f32_e32 v217, v41, v6
	v_lshlrev_b32_e32 v7, 16, v160
	v_and_b32_e32 v8, 0xffff0000, v160
	v_fmac_f32_e32 v218, v24, v7
	v_fmac_f32_e32 v219, v40, v7
	v_fmac_f32_e32 v218, v25, v8
	v_fmac_f32_e32 v219, v41, v8
	v_lshlrev_b32_e32 v5, 16, v137
	v_and_b32_e32 v6, 0xffff0000, v137
	v_fmac_f32_e32 v212, v26, v5
	v_fmac_f32_e32 v213, v42, v5
	v_fmac_f32_e32 v212, v27, v6
	v_fmac_f32_e32 v213, v43, v6
	v_lshlrev_b32_e32 v7, 16, v145
	v_and_b32_e32 v8, 0xffff0000, v145
	v_fmac_f32_e32 v214, v26, v7
	v_fmac_f32_e32 v215, v42, v7
	v_fmac_f32_e32 v214, v27, v8
	v_fmac_f32_e32 v215, v43, v8
	v_lshlrev_b32_e32 v5, 16, v153
	v_and_b32_e32 v6, 0xffff0000, v153
	v_fmac_f32_e32 v216, v26, v5
	v_fmac_f32_e32 v217, v42, v5
	v_fmac_f32_e32 v216, v27, v6
	v_fmac_f32_e32 v217, v43, v6
	v_lshlrev_b32_e32 v7, 16, v161
	v_and_b32_e32 v8, 0xffff0000, v161
	v_fmac_f32_e32 v218, v26, v7
	v_fmac_f32_e32 v219, v42, v7
	v_fmac_f32_e32 v218, v27, v8
	v_fmac_f32_e32 v219, v43, v8
	v_lshlrev_b32_e32 v5, 16, v138
	v_and_b32_e32 v6, 0xffff0000, v138
	v_fmac_f32_e32 v212, v28, v5
	v_fmac_f32_e32 v213, v44, v5
	v_fmac_f32_e32 v212, v29, v6
	v_fmac_f32_e32 v213, v45, v6
	v_lshlrev_b32_e32 v7, 16, v146
	v_and_b32_e32 v8, 0xffff0000, v146
	v_fmac_f32_e32 v214, v28, v7
	v_fmac_f32_e32 v215, v44, v7
	v_fmac_f32_e32 v214, v29, v8
	v_fmac_f32_e32 v215, v45, v8
	v_lshlrev_b32_e32 v5, 16, v154
	v_and_b32_e32 v6, 0xffff0000, v154
	v_fmac_f32_e32 v216, v28, v5
	v_fmac_f32_e32 v217, v44, v5
	v_fmac_f32_e32 v216, v29, v6
	v_fmac_f32_e32 v217, v45, v6
	v_lshlrev_b32_e32 v7, 16, v162
	v_and_b32_e32 v8, 0xffff0000, v162
	v_fmac_f32_e32 v218, v28, v7
	v_fmac_f32_e32 v219, v44, v7
	v_fmac_f32_e32 v218, v29, v8
	v_fmac_f32_e32 v219, v45, v8
	v_lshlrev_b32_e32 v5, 16, v139
	v_and_b32_e32 v6, 0xffff0000, v139
	v_fmac_f32_e32 v212, v30, v5
	v_fmac_f32_e32 v213, v46, v5
	v_fmac_f32_e32 v212, v31, v6
	v_fmac_f32_e32 v213, v47, v6
	v_lshlrev_b32_e32 v7, 16, v147
	v_and_b32_e32 v8, 0xffff0000, v147
	v_fmac_f32_e32 v214, v30, v7
	v_fmac_f32_e32 v215, v46, v7
	v_fmac_f32_e32 v214, v31, v8
	v_fmac_f32_e32 v215, v47, v8
	v_lshlrev_b32_e32 v5, 16, v155
	v_and_b32_e32 v6, 0xffff0000, v155
	v_fmac_f32_e32 v216, v30, v5
	v_fmac_f32_e32 v217, v46, v5
	v_fmac_f32_e32 v216, v31, v6
	v_fmac_f32_e32 v217, v47, v6
	v_lshlrev_b32_e32 v7, 16, v163
	v_and_b32_e32 v8, 0xffff0000, v163
	v_fmac_f32_e32 v218, v30, v7
	v_fmac_f32_e32 v219, v46, v7
	v_fmac_f32_e32 v218, v31, v8
	v_fmac_f32_e32 v219, v47, v8
	v_add_f32_dpp v212, v212, v212 quad_perm:[1,0,3,2] row_mask:0xf bank_mask:0xf
	v_add_f32_dpp v213, v213, v213 quad_perm:[1,0,3,2] row_mask:0xf bank_mask:0xf
	v_add_f32_dpp v214, v214, v214 quad_perm:[1,0,3,2] row_mask:0xf bank_mask:0xf
	v_add_f32_dpp v215, v215, v215 quad_perm:[1,0,3,2] row_mask:0xf bank_mask:0xf
	v_add_f32_dpp v216, v216, v216 quad_perm:[1,0,3,2] row_mask:0xf bank_mask:0xf
	v_add_f32_dpp v217, v217, v217 quad_perm:[1,0,3,2] row_mask:0xf bank_mask:0xf
	v_add_f32_dpp v218, v218, v218 quad_perm:[1,0,3,2] row_mask:0xf bank_mask:0xf
	v_add_f32_dpp v219, v219, v219 quad_perm:[1,0,3,2] row_mask:0xf bank_mask:0xf
	v_add_f32_dpp v212, v212, v212 quad_perm:[2,3,0,1] row_mask:0xf bank_mask:0xf
	v_add_f32_dpp v213, v213, v213 quad_perm:[2,3,0,1] row_mask:0xf bank_mask:0xf
	v_add_f32_dpp v214, v214, v214 quad_perm:[2,3,0,1] row_mask:0xf bank_mask:0xf
	v_add_f32_dpp v215, v215, v215 quad_perm:[2,3,0,1] row_mask:0xf bank_mask:0xf
	v_add_f32_dpp v216, v216, v216 quad_perm:[2,3,0,1] row_mask:0xf bank_mask:0xf
	v_add_f32_dpp v217, v217, v217 quad_perm:[2,3,0,1] row_mask:0xf bank_mask:0xf
	v_add_f32_dpp v218, v218, v218 quad_perm:[2,3,0,1] row_mask:0xf bank_mask:0xf
	v_add_f32_dpp v219, v219, v219 quad_perm:[2,3,0,1] row_mask:0xf bank_mask:0xf
	v_add_f32_dpp v212, v212, v212 row_half_mirror row_mask:0xf bank_mask:0xf
	v_add_f32_dpp v213, v213, v213 row_half_mirror row_mask:0xf bank_mask:0xf
	v_add_f32_dpp v214, v214, v214 row_half_mirror row_mask:0xf bank_mask:0xf
	v_add_f32_dpp v215, v215, v215 row_half_mirror row_mask:0xf bank_mask:0xf
	v_add_f32_dpp v216, v216, v216 row_half_mirror row_mask:0xf bank_mask:0xf
	v_add_f32_dpp v217, v217, v217 row_half_mirror row_mask:0xf bank_mask:0xf
	v_add_f32_dpp v218, v218, v218 row_half_mirror row_mask:0xf bank_mask:0xf
	v_add_f32_dpp v219, v219, v219 row_half_mirror row_mask:0xf bank_mask:0xf
	v_add_f32_dpp v212, v212, v212 row_mirror row_mask:0xf bank_mask:0xf
	v_add_f32_dpp v213, v213, v213 row_mirror row_mask:0xf bank_mask:0xf
	v_add_f32_dpp v214, v214, v214 row_mirror row_mask:0xf bank_mask:0xf
	v_add_f32_dpp v215, v215, v215 row_mirror row_mask:0xf bank_mask:0xf
	v_add_f32_dpp v216, v216, v216 row_mirror row_mask:0xf bank_mask:0xf
	v_add_f32_dpp v217, v217, v217 row_mirror row_mask:0xf bank_mask:0xf
	v_add_f32_dpp v218, v218, v218 row_mirror row_mask:0xf bank_mask:0xf
	v_add_f32_dpp v219, v219, v219 row_mirror row_mask:0xf bank_mask:0xf
	v_add_f32_dpp v212, v212, v212 row_bcast:15 row_mask:0xa bank_mask:0xf
	v_add_f32_dpp v213, v213, v213 row_bcast:15 row_mask:0xa bank_mask:0xf
	v_add_f32_dpp v214, v214, v214 row_bcast:15 row_mask:0xa bank_mask:0xf
	v_add_f32_dpp v215, v215, v215 row_bcast:15 row_mask:0xa bank_mask:0xf
	v_add_f32_dpp v216, v216, v216 row_bcast:15 row_mask:0xa bank_mask:0xf
	v_add_f32_dpp v217, v217, v217 row_bcast:15 row_mask:0xa bank_mask:0xf
	v_add_f32_dpp v218, v218, v218 row_bcast:15 row_mask:0xa bank_mask:0xf
	v_add_f32_dpp v219, v219, v219 row_bcast:15 row_mask:0xa bank_mask:0xf
	v_add_f32_dpp v212, v212, v212 row_bcast:31 row_mask:0xc bank_mask:0xf
	v_add_f32_dpp v213, v213, v213 row_bcast:31 row_mask:0xc bank_mask:0xf
	v_add_f32_dpp v214, v214, v214 row_bcast:31 row_mask:0xc bank_mask:0xf
	v_add_f32_dpp v215, v215, v215 row_bcast:31 row_mask:0xc bank_mask:0xf
	v_add_f32_dpp v216, v216, v216 row_bcast:31 row_mask:0xc bank_mask:0xf
	v_add_f32_dpp v217, v217, v217 row_bcast:31 row_mask:0xc bank_mask:0xf
	v_add_f32_dpp v218, v218, v218 row_bcast:31 row_mask:0xc bank_mask:0xf
	v_add_f32_dpp v219, v219, v219 row_bcast:31 row_mask:0xc bank_mask:0xf
	s_nop 0
	v_readlane_b32 s32, v212, 63
	v_readlane_b32 s33, v213, 63
	v_readlane_b32 s40, v214, 63
	v_readlane_b32 s41, v215, 63
	v_readlane_b32 s46, v216, 63
	v_readlane_b32 s47, v217, 63
	v_readlane_b32 s51, v218, 63
	v_readlane_b32 s57, v219, 63
	s_nop 1
	v_writelane_b32 v9, s32, 0
	v_writelane_b32 v9, s33, 1
	v_writelane_b32 v9, s40, 2
	v_writelane_b32 v9, s41, 3
	v_writelane_b32 v9, s46, 4
	v_writelane_b32 v9, s47, 5
	v_writelane_b32 v9, s51, 6
	v_writelane_b32 v9, s57, 7
	s_mul_i32 s91, s3, 11264
	s_add_i32 s91, s91, s5
	s_add_i32 s91, s91, 4608
	s_add_u32 s8, s0, 0x3e00000
	s_addc_u32 s9, s1, 0
	v_add_u32_e32 v15, s91, v14
	v_lshlrev_b32_e32 v15, 2, v15
	s_mov_b64 exec, 0xff
	global_store_dword v15, v9, s[8:9]
	s_mov_b64 exec, -1

.LBB0_493:
	s_waitcnt lgkmcnt(0)
	v_readfirstlane_b32 s2, v2
	v_readfirstlane_b32 s3, v0
	s_xor_b32 s2, s2, 32
	s_xor_b32 s3, s3, 1
	s_or_b32 s2, s2, s3
	s_cmp_lg_u32 s2, 0
	s_cbranch_scc1 .Lsplit1_full
	v_readlane_b32 s2, v254, 8
	v_readlane_b32 s3, v254, 9
	v_readlane_b32 s4, v254, 20
	v_mov_b32_e32 v16, 0
	s_and_b32 s4, s4, 7
	s_lshl_b32 s4, s4, 8
	s_add_u32 s2, s2, s4
	s_addc_u32 s3, s3, 0
.Lsplit1_poll:
	global_load_dword v17, v16, s[2:3] offset:2112 sc1
	s_waitcnt vmcnt(0)
	v_readfirstlane_b32 s4, v17
	s_cmpk_lt_u32 s4, 0x100
	s_cbranch_scc0 .Lsplit1_got
	s_sleep 1
	s_branch .Lsplit1_poll
.Lsplit1_got:
	s_waitcnt lgkmcnt(0)
	buffer_inv sc1
	s_waitcnt vmcnt(0)
	s_branch .LBB0_529
